# attention: remaining end-of-tile exps retargeted to free registers (consumers in next tile renamed) and spread over PV groups 0-1, on top of v32
# baseline (speedup 1.0000x reference)
; __device__ __forceinline__ void finishSM(f32x16& p0, f32x16& p1, float alpha, float& l_reg, bf16x8& pa0, bf16x8& pa1, bf16x8& pa2, bf16x8& pa3) {
;   for (int r = 0; r < 16; ++r) p1[r] = __builtin_amdgcn_exp2f(p1[r]);
;   float ps = 0; for (int r = 0; r < 16; ++r) ps += p0[r]; for (int r = 0; r < 16; ++r) ps += p1[r];
;   { auto rr = __builtin_amdgcn_permlane32_swap(__float_as_uint(ps), __float_as_uint(ps), false, false);
;     ps = __uint_as_float(rr[0]) + __uint_as_float(rr[1]); }
;   l_reg = l_reg * alpha + ps;
;     ...
;   PK4(p0, 0, pa0); PK4(p0, 8, pa1); PK4(p1, 0, pa2); PK4(p1, 8, pa3);
;     ...
; }
.LBB0_352:
	s_waitcnt lgkmcnt(0)
	s_barrier
	ds_read_b128 v[80:83], v207 offset:16384
	ds_read_b128 v[84:87], v207 offset:24576
	ds_read_b128 v[162:165], v208 offset:16384
	ds_read_b128 v[166:169], v208 offset:24576
	v_exp_f32_e32 v170, v72
	v_exp_f32_e32 v171, v73
	v_exp_f32_e32 v172, v74
	v_exp_f32_e32 v173, v75
	v_exp_f32_e32 v174, v76
	v_exp_f32_e32 v175, v77
	v_exp_f32_e32 v176, v78
	v_exp_f32_e32 v79, v79
	s_waitcnt lgkmcnt(3)
	v_mfma_f32_32x32x16_bf16 v[96:111], v[80:83], v[142:145], 0
	v_exp_f32_e32 v236, v64
	v_add_f32_e32 v64, 0, v229
	v_add_f32_e32 v64, v243, v64
	v_add_f32_e32 v64, v244, v64
	s_waitcnt lgkmcnt(2)
	v_mfma_f32_32x32x16_bf16 v[80:95], v[84:87], v[142:145], 0
	v_add_f32_e32 v64, v246, v64
	v_add_f32_e32 v64, v242, v64
	v_add_f32_e32 v64, v245, v64
	s_waitcnt lgkmcnt(1)
	v_mfma_f32_32x32x16_bf16 v[96:111], v[162:165], v[138:141], v[96:111]
	v_add_f32_e32 v64, v227, v64
	v_add_f32_e32 v64, v228, v64
	v_add_f32_e32 v64, v223, v64
	s_waitcnt lgkmcnt(0)
	v_mfma_f32_32x32x16_bf16 v[80:95], v[166:169], v[138:141], v[80:95]
	ds_read_b128 v[162:165], v209 offset:16384
	ds_read_b128 v[166:169], v209 offset:24576
	v_add_f32_e32 v64, v226, v64
	v_add_f32_e32 v64, v224, v64
	v_add_f32_e32 v64, v225, v64
	v_add_f32_e32 v64, v220, v64
	v_exp_f32_e32 v237, v65
	s_waitcnt lgkmcnt(1)
	v_mfma_f32_32x32x16_bf16 v[96:111], v[162:165], v[112:115], v[96:111]
	v_add_f32_e32 v64, v222, v64
	v_exp_f32_e32 v238, v66
	v_add_f32_e32 v64, v219, v64
	v_exp_f32_e32 v239, v67
	s_waitcnt lgkmcnt(0)
	v_mfma_f32_32x32x16_bf16 v[80:95], v[166:169], v[112:115], v[80:95]
	ds_read_b128 v[162:165], v210 offset:16384
	ds_read_b128 v[166:169], v210 offset:24576
	v_add_f32_e32 v64, v221, v64
	v_exp_f32_e32 v247, v68
	v_add_f32_e32 v64, v236, v64
	v_exp_f32_e32 v248, v69
	s_waitcnt lgkmcnt(1)
	v_mfma_f32_32x32x16_bf16 v[96:111], v[162:165], v[116:119], v[96:111]
	v_add_f32_e32 v64, v237, v64
	v_exp_f32_e32 v249, v70
	v_add_f32_e32 v64, v238, v64
	v_exp_f32_e32 v252, v71
	s_waitcnt lgkmcnt(0)
	v_mfma_f32_32x32x16_bf16 v[80:95], v[166:169], v[116:119], v[80:95]
	ds_read_b128 v[162:165], v190 offset:16384
	ds_read_b128 v[166:169], v190 offset:24576
	v_add_f32_e32 v64, v239, v64
	v_add_f32_e32 v64, v247, v64
	v_add_f32_e32 v64, v248, v64
	v_add_f32_e32 v64, v249, v64
	v_add_f32_e32 v64, v252, v64
	v_add_f32_e32 v64, v170, v64
	s_waitcnt lgkmcnt(1)
	v_mfma_f32_32x32x16_bf16 v[96:111], v[162:165], v[120:123], v[96:111]
	v_add_f32_e32 v64, v171, v64
	v_add_f32_e32 v64, v172, v64
	v_add_f32_e32 v64, v173, v64
	v_add_f32_e32 v64, v174, v64
	v_add_f32_e32 v64, v175, v64
	s_waitcnt lgkmcnt(0)
	v_mfma_f32_32x32x16_bf16 v[80:95], v[166:169], v[120:123], v[80:95]
	ds_read_b128 v[162:165], v191 offset:16384
	ds_read_b128 v[166:169], v191 offset:24576
	v_add_f32_e32 v64, v176, v64
	v_add_f32_e32 v64, v79, v64
	v_mov_b32_e32 v65, v64
	s_nop 1
	v_permlane32_swap_b32_e32 v64, v65
	v_add_f32_e32 v64, v64, v65
	s_waitcnt lgkmcnt(1)
	v_mfma_f32_32x32x16_bf16 v[96:111], v[162:165], v[124:127], v[96:111]
	v_add_f32_e32 v128, v215, v64
	v_cvt_pk_bf16_f32 v64, v229, v243
	v_cvt_pk_bf16_f32 v65, v244, v246
	v_cvt_pk_bf16_f32 v66, v242, v245
	v_cvt_pk_bf16_f32 v67, v227, v228
	s_waitcnt lgkmcnt(0)
	v_mfma_f32_32x32x16_bf16 v[80:95], v[166:169], v[124:127], v[80:95]
	ds_read_b128 v[162:165], v192 offset:16384
	ds_read_b128 v[166:169], v192 offset:24576
	v_cvt_pk_bf16_f32 v68, v223, v226
	v_cvt_pk_bf16_f32 v69, v224, v225
	v_cvt_pk_bf16_f32 v70, v220, v222
	v_cvt_pk_bf16_f32 v71, v219, v221
	v_cvt_pk_bf16_f32 v72, v236, v237
	v_cvt_pk_bf16_f32 v73, v238, v239
	s_waitcnt lgkmcnt(1)
	v_mfma_f32_32x32x16_bf16 v[96:111], v[162:165], v[130:133], v[96:111]
	v_cvt_pk_bf16_f32 v74, v247, v248
	v_cvt_pk_bf16_f32 v75, v249, v252
	v_cvt_pk_bf16_f32 v76, v170, v171
	v_cvt_pk_bf16_f32 v77, v172, v173
	v_cvt_pk_bf16_f32 v78, v174, v175
	s_waitcnt lgkmcnt(0)
	v_mfma_f32_32x32x16_bf16 v[80:95], v[166:169], v[130:133], v[80:95]
	ds_read_b128 v[162:165], v193 offset:16384
	ds_read_b128 v[166:169], v193 offset:24576
	ds_read_b64_tr_b16 v[180:181], v206 offset:0
	ds_read_b64_tr_b16 v[182:183], v206 offset:0x800
	ds_read_b64_tr_b16 v[184:185], v206 offset:0x1000
	ds_read_b64_tr_b16 v[186:187], v206 offset:0x1800
	ds_read_b64_tr_b16 v[216:217], v206 offset:0x2000
	ds_read_b64_tr_b16 v[218:219], v206 offset:0x2800
	ds_read_b64_tr_b16 v[220:221], v206 offset:0x3000
	ds_read_b64_tr_b16 v[222:223], v206 offset:0x3800
	v_cvt_pk_bf16_f32 v79, v176, v79
	s_nop 0
	v_permlane32_swap_b32_e32 v64, v66
	v_permlane32_swap_b32_e32 v65, v67
	v_permlane32_swap_b32_e32 v68, v70
	v_permlane32_swap_b32_e32 v69, v71
	s_waitcnt lgkmcnt(9)
	v_mfma_f32_32x32x16_bf16 v[96:111], v[162:165], v[134:137], v[96:111]
	v_permlane32_swap_b32_e32 v72, v74
	v_permlane32_swap_b32_e32 v73, v75
	v_permlane32_swap_b32_e32 v76, v78
	v_permlane32_swap_b32_e32 v77, v79
	s_waitcnt lgkmcnt(8)
	v_mfma_f32_32x32x16_bf16 v[80:95], v[166:169], v[134:137], v[80:95]
	s_waitcnt vmcnt(0)
	ds_write_b128 v211, v[146:149] offset:32768
	s_nop 0
	s_waitcnt lgkmcnt(7)
	v_mfma_f32_32x32x16_bf16 v[0:15], v[64:67], v[180:183], v[0:15]
	ds_read_b64_tr_b16 v[180:181], v206 offset:0x200
	ds_read_b64_tr_b16 v[182:183], v206 offset:0xa00
	v_add_co_u32_e32 v166, vcc, s19, v178
	s_nop 1
	v_addc_co_u32_e32 v167, vcc, -1, v179, vcc
	v_add_co_u32_e32 v170, vcc, s20, v178
	s_nop 1
	v_addc_co_u32_e32 v171, vcc, -1, v179, vcc
	s_waitcnt lgkmcnt(7)
	v_mfma_f32_32x32x16_bf16 v[0:15], v[68:71], v[184:187], v[0:15]
	ds_read_b64_tr_b16 v[184:185], v206 offset:0x1200
	ds_read_b64_tr_b16 v[186:187], v206 offset:0x1a00
	global_load_dwordx4 v[162:165], v[166:167], off
	s_nop 0
	global_load_dwordx4 v[166:169], v[166:167], off offset:-512
	s_nop 0
	global_load_dwordx4 v[174:177], v[170:171], off
	s_nop 0
	global_load_dwordx4 v[170:173], v[170:171], off offset:-512
	s_waitcnt lgkmcnt(7)
; #define SBAR() __builtin_amdgcn_sched_barrier(0)
; template <int D0, int BOFF> __device__ __forceinline__ void pv_one_i(f32x16& od, int vb, bf16x8 pa0, bf16x8 pa1, bf16x8 pa2, bf16x8 pa3) {
;   const s16x4 l0 = tr_read<BOFF + v_rd_off(D0, 0, 0)>(vb), h0 = tr_read<BOFF + v_rd_off(D0, 0, 1)>(vb), l1 = tr_read<BOFF + v_rd_off(D0, 1, 0)>(vb), h1 = tr_read<BOFF + v_rd_off(D0, 1, 1)>(vb);
;   const s16x4 l2 = tr_read<BOFF + v_rd_off(D0, 2, 0)>(vb), h2 = tr_read<BOFF + v_rd_off(D0, 2, 1)>(vb), l3 = tr_read<BOFF + v_rd_off(D0, 3, 0)>(vb), h3 = tr_read<BOFF + v_rd_off(D0, 3, 1)>(vb);
;   asm volatile("s_waitcnt lgkmcnt(0)" ::: "memory"); SBAR();
;     ...
;   od = __builtin_amdgcn_mfma_f32_32x32x16_bf16(pa0, PK(l0, h0), od, 0, 0, 0);
;   od = __builtin_amdgcn_mfma_f32_32x32x16_bf16(pa1, PK(l1, h1), od, 0, 0, 0);
;   od = __builtin_amdgcn_mfma_f32_32x32x16_bf16(pa2, PK(l2, h2), od, 0, 0, 0);
;   od = __builtin_amdgcn_mfma_f32_32x32x16_bf16(pa3, PK(l3, h3), od, 0, 0, 0);
;     ...
; }
; template <int BOFF> __device__ __forceinline__ void pv_i(f32x16* o, int vb, bf16x8 pa0, bf16x8 pa1, bf16x8 pa2, bf16x8 pa3) {
;   pv_one_i<0, BOFF>(o[0], vb, pa0, pa1, pa2, pa3); pv_one_i<1, BOFF>(o[1], vb, pa0, pa1, pa2, pa3); pv_one_i<2, BOFF>(o[2], vb, pa0, pa1, pa2, pa3); pv_one_i<3, BOFF>(o[3], vb, pa0, pa1, pa2, pa3);
; }
	v_mfma_f32_32x32x16_bf16 v[0:15], v[72:75], v[216:219], v[0:15]
	ds_read_b64_tr_b16 v[216:217], v206 offset:0x2200
	ds_read_b64_tr_b16 v[218:219], v206 offset:0x2a00
	v_exp_f32_e32 v200, v96
	v_exp_f32_e32 v240, v109
	s_waitcnt lgkmcnt(7)
	v_mfma_f32_32x32x16_bf16 v[0:15], v[76:79], v[220:223], v[0:15]
	ds_read_b64_tr_b16 v[220:221], v206 offset:0x3200
	ds_read_b64_tr_b16 v[222:223], v206 offset:0x3a00
	v_exp_f32_e32 v201, v97
	v_exp_f32_e32 v241, v110
	ds_write_b128 v212, v[150:153] offset:32768
	s_waitcnt lgkmcnt(7)
	v_mfma_f32_32x32x16_bf16 v[16:31], v[64:67], v[180:183], v[16:31]
	ds_read_b64_tr_b16 v[180:181], v206 offset:0x400
	ds_read_b64_tr_b16 v[182:183], v206 offset:0xc00
	v_exp_f32_e32 v202, v98
	v_exp_f32_e32 v250, v111
	s_waitcnt lgkmcnt(7)
	v_mfma_f32_32x32x16_bf16 v[16:31], v[68:71], v[184:187], v[16:31]
	ds_read_b64_tr_b16 v[184:185], v206 offset:0x1400
	ds_read_b64_tr_b16 v[186:187], v206 offset:0x1c00
	v_exp_f32_e32 v203, v99
	s_waitcnt lgkmcnt(7)
	v_mfma_f32_32x32x16_bf16 v[16:31], v[72:75], v[216:219], v[16:31]
	ds_read_b64_tr_b16 v[216:217], v206 offset:0x2400
	ds_read_b64_tr_b16 v[218:219], v206 offset:0x2c00
	v_exp_f32_e32 v204, v100
	s_waitcnt lgkmcnt(7)
	v_mfma_f32_32x32x16_bf16 v[16:31], v[76:79], v[220:223], v[16:31]
	ds_read_b64_tr_b16 v[220:221], v206 offset:0x3400
	ds_read_b64_tr_b16 v[222:223], v206 offset:0x3c00
	v_exp_f32_e32 v205, v101
	ds_write_b128 v213, v[154:157] offset:32768
	s_waitcnt lgkmcnt(7)
	v_mfma_f32_32x32x16_bf16 v[32:47], v[64:67], v[180:183], v[32:47]
	ds_read_b64_tr_b16 v[180:181], v206 offset:0x600
	ds_read_b64_tr_b16 v[182:183], v206 offset:0xe00
	v_exp_f32_e32 v215, v108
	v_exp_f32_e32 v188, v102
	s_waitcnt lgkmcnt(7)
	v_mfma_f32_32x32x16_bf16 v[32:47], v[68:71], v[184:187], v[32:47]
	ds_read_b64_tr_b16 v[184:185], v206 offset:0x1600
	ds_read_b64_tr_b16 v[186:187], v206 offset:0x1e00
	v_exp_f32_e32 v189, v103
	v_exp_f32_e32 v196, v104
	s_waitcnt lgkmcnt(7)
	v_mfma_f32_32x32x16_bf16 v[32:47], v[72:75], v[216:219], v[32:47]
	ds_read_b64_tr_b16 v[216:217], v206 offset:0x2600
	ds_read_b64_tr_b16 v[218:219], v206 offset:0x2e00
	v_exp_f32_e32 v197, v105
	v_exp_f32_e32 v198, v106
	s_waitcnt lgkmcnt(7)
	v_mfma_f32_32x32x16_bf16 v[32:47], v[76:79], v[220:223], v[32:47]
	ds_read_b64_tr_b16 v[220:221], v206 offset:0x3600
	ds_read_b64_tr_b16 v[222:223], v206 offset:0x3e00
	v_exp_f32_e32 v199, v107
	ds_write_b128 v214, v[158:161] offset:32768
	s_waitcnt lgkmcnt(7)
	v_mfma_f32_32x32x16_bf16 v[48:63], v[64:67], v[180:183], v[48:63]
	s_waitcnt vmcnt(4)
	s_waitcnt lgkmcnt(5)
	v_mfma_f32_32x32x16_bf16 v[48:63], v[68:71], v[184:187], v[48:63]
	s_waitcnt lgkmcnt(3)
	v_mfma_f32_32x32x16_bf16 v[48:63], v[72:75], v[216:219], v[48:63]
	s_waitcnt lgkmcnt(0)
	s_barrier
	v_mfma_f32_32x32x16_bf16 v[48:63], v[76:79], v[220:223], v[48:63]
	ds_read_b128 v[64:67], v207 offset:32768
	ds_read_b128 v[96:99], v207 offset:40960
	ds_read_b128 v[146:149], v208 offset:32768
	ds_read_b128 v[150:153], v208 offset:40960
	v_exp_f32_e32 v154, v88
	v_exp_f32_e32 v155, v89
	v_exp_f32_e32 v156, v90
	v_exp_f32_e32 v157, v91
	v_exp_f32_e32 v158, v92
	v_exp_f32_e32 v159, v93
	v_exp_f32_e32 v160, v94
	v_exp_f32_e32 v95, v95
	s_waitcnt lgkmcnt(3)
	v_mfma_f32_32x32x16_bf16 v[64:79], v[64:67], v[142:145], 0
	v_exp_f32_e32 v236, v80
	v_add_f32_e32 v80, 0, v200
	v_add_f32_e32 v80, v201, v80
	v_add_f32_e32 v80, v202, v80
	s_waitcnt lgkmcnt(2)
	v_mfma_f32_32x32x16_bf16 v[96:111], v[96:99], v[142:145], 0
	v_add_f32_e32 v80, v203, v80
	v_add_f32_e32 v80, v204, v80
	v_add_f32_e32 v80, v205, v80
	s_waitcnt lgkmcnt(1)
	v_mfma_f32_32x32x16_bf16 v[64:79], v[146:149], v[138:141], v[64:79]
	v_add_f32_e32 v80, v188, v80
	v_add_f32_e32 v80, v189, v80
	v_add_f32_e32 v80, v196, v80
	s_waitcnt lgkmcnt(0)
	v_mfma_f32_32x32x16_bf16 v[96:111], v[150:153], v[138:141], v[96:111]
	ds_read_b128 v[146:149], v209 offset:32768
	ds_read_b128 v[150:153], v209 offset:40960
	v_add_f32_e32 v80, v197, v80
	v_add_f32_e32 v80, v198, v80
	v_add_f32_e32 v80, v199, v80
	v_add_f32_e32 v80, v215, v80
	v_exp_f32_e32 v237, v81
	s_waitcnt lgkmcnt(1)
	v_mfma_f32_32x32x16_bf16 v[64:79], v[146:149], v[112:115], v[64:79]
	v_add_f32_e32 v80, v240, v80
	v_exp_f32_e32 v238, v82
	v_add_f32_e32 v80, v241, v80
	v_exp_f32_e32 v239, v83
	s_waitcnt lgkmcnt(0)
	v_mfma_f32_32x32x16_bf16 v[96:111], v[150:153], v[112:115], v[96:111]
	ds_read_b128 v[146:149], v210 offset:32768
	ds_read_b128 v[150:153], v210 offset:40960
	v_add_f32_e32 v80, v250, v80
	v_exp_f32_e32 v247, v84
	v_add_f32_e32 v80, v236, v80
	v_exp_f32_e32 v248, v85
	s_waitcnt lgkmcnt(1)
	v_mfma_f32_32x32x16_bf16 v[64:79], v[146:149], v[116:119], v[64:79]
	v_add_f32_e32 v80, v237, v80
	v_exp_f32_e32 v249, v86
	v_add_f32_e32 v80, v238, v80
	v_exp_f32_e32 v252, v87
	s_waitcnt lgkmcnt(0)
	v_mfma_f32_32x32x16_bf16 v[96:111], v[150:153], v[116:119], v[96:111]
	ds_read_b128 v[146:149], v190 offset:32768
	ds_read_b128 v[150:153], v190 offset:40960
	v_add_f32_e32 v80, v239, v80
	v_add_f32_e32 v80, v247, v80
	v_add_f32_e32 v80, v248, v80
	v_add_f32_e32 v80, v249, v80
	v_add_f32_e32 v80, v252, v80
	v_add_f32_e32 v80, v154, v80
	s_waitcnt lgkmcnt(1)
	v_mfma_f32_32x32x16_bf16 v[64:79], v[146:149], v[120:123], v[64:79]
	v_add_f32_e32 v80, v155, v80
	v_add_f32_e32 v80, v156, v80
	v_add_f32_e32 v80, v157, v80
	v_add_f32_e32 v80, v158, v80
	v_add_f32_e32 v80, v159, v80
	s_waitcnt lgkmcnt(0)
	v_mfma_f32_32x32x16_bf16 v[96:111], v[150:153], v[120:123], v[96:111]
	ds_read_b128 v[146:149], v191 offset:32768
	ds_read_b128 v[150:153], v191 offset:40960
	v_add_f32_e32 v80, v160, v80
	v_add_f32_e32 v180, v95, v80
	v_mov_b32_e32 v182, v180
	v_cvt_pk_bf16_f32 v80, v200, v201
	v_cvt_pk_bf16_f32 v81, v202, v203
	v_cvt_pk_bf16_f32 v82, v204, v205
	s_waitcnt lgkmcnt(1)
; #define SBAR() __builtin_amdgcn_sched_barrier(0)
; __device__ __forceinline__ void finishSM(f32x16& p0, f32x16& p1, float alpha, float& l_reg, bf16x8& pa0, bf16x8& pa1, bf16x8& pa2, bf16x8& pa3) {
;   for (int r = 0; r < 16; ++r) p1[r] = __builtin_amdgcn_exp2f(p1[r]);
;   float ps = 0; for (int r = 0; r < 16; ++r) ps += p0[r]; for (int r = 0; r < 16; ++r) ps += p1[r];
;   { auto rr = __builtin_amdgcn_permlane32_swap(__float_as_uint(ps), __float_as_uint(ps), false, false);
;     ps = __uint_as_float(rr[0]) + __uint_as_float(rr[1]); }
;   l_reg = l_reg * alpha + ps;
;     ...
;   PK4(p0, 0, pa0); PK4(p0, 8, pa1); PK4(p1, 0, pa2); PK4(p1, 8, pa3);
;     ...
; }
; template <int D0, int BOFF> __device__ __forceinline__ void pv_one_i(f32x16& od, int vb, bf16x8 pa0, bf16x8 pa1, bf16x8 pa2, bf16x8 pa3) {
;   const s16x4 l0 = tr_read<BOFF + v_rd_off(D0, 0, 0)>(vb), h0 = tr_read<BOFF + v_rd_off(D0, 0, 1)>(vb), l1 = tr_read<BOFF + v_rd_off(D0, 1, 0)>(vb), h1 = tr_read<BOFF + v_rd_off(D0, 1, 1)>(vb);
;   const s16x4 l2 = tr_read<BOFF + v_rd_off(D0, 2, 0)>(vb), h2 = tr_read<BOFF + v_rd_off(D0, 2, 1)>(vb), l3 = tr_read<BOFF + v_rd_off(D0, 3, 0)>(vb), h3 = tr_read<BOFF + v_rd_off(D0, 3, 1)>(vb);
;   asm volatile("s_waitcnt lgkmcnt(0)" ::: "memory"); SBAR();
;     ...
;   od = __builtin_amdgcn_mfma_f32_32x32x16_bf16(pa0, PK(l0, h0), od, 0, 0, 0);
;   od = __builtin_amdgcn_mfma_f32_32x32x16_bf16(pa1, PK(l1, h1), od, 0, 0, 0);
;   od = __builtin_amdgcn_mfma_f32_32x32x16_bf16(pa2, PK(l2, h2), od, 0, 0, 0);
;   od = __builtin_amdgcn_mfma_f32_32x32x16_bf16(pa3, PK(l3, h3), od, 0, 0, 0);
;     ...
; }
; template <int BOFF> __device__ __forceinline__ void pv_i(f32x16* o, int vb, bf16x8 pa0, bf16x8 pa1, bf16x8 pa2, bf16x8 pa3) {
;   pv_one_i<0, BOFF>(o[0], vb, pa0, pa1, pa2, pa3); pv_one_i<1, BOFF>(o[1], vb, pa0, pa1, pa2, pa3); pv_one_i<2, BOFF>(o[2], vb, pa0, pa1, pa2, pa3); pv_one_i<3, BOFF>(o[3], vb, pa0, pa1, pa2, pa3);
; }
	v_mfma_f32_32x32x16_bf16 v[64:79], v[146:149], v[124:127], v[64:79]
	v_cvt_pk_bf16_f32 v83, v188, v189
	v_cvt_pk_bf16_f32 v84, v196, v197
	v_cvt_pk_bf16_f32 v85, v198, v199
	v_cvt_pk_bf16_f32 v86, v215, v240
	v_cvt_pk_bf16_f32 v87, v241, v250
	s_waitcnt lgkmcnt(0)
	v_mfma_f32_32x32x16_bf16 v[96:111], v[150:153], v[124:127], v[96:111]
	ds_read_b128 v[146:149], v192 offset:32768
	ds_read_b128 v[150:153], v192 offset:40960
	v_cvt_pk_bf16_f32 v88, v236, v237
	v_cvt_pk_bf16_f32 v89, v238, v239
	v_cvt_pk_bf16_f32 v90, v247, v248
	v_cvt_pk_bf16_f32 v91, v249, v252
	v_cvt_pk_bf16_f32 v92, v154, v155
	v_cvt_pk_bf16_f32 v93, v156, v157
	s_waitcnt lgkmcnt(1)
	v_mfma_f32_32x32x16_bf16 v[64:79], v[146:149], v[130:133], v[64:79]
	v_cvt_pk_bf16_f32 v94, v158, v159
	v_cvt_pk_bf16_f32 v95, v160, v95
	s_nop 1
	v_permlane32_swap_b32_e32 v180, v182
	v_permlane32_swap_b32_e32 v80, v82
	s_waitcnt lgkmcnt(0)
	v_mfma_f32_32x32x16_bf16 v[96:111], v[150:153], v[130:133], v[96:111]
	ds_read_b128 v[146:149], v193 offset:32768
	ds_read_b128 v[150:153], v193 offset:40960
	ds_read_b64_tr_b16 v[184:185], v206 offset:0x4000
	ds_read_b64_tr_b16 v[186:187], v206 offset:0x4800
	ds_read_b64_tr_b16 v[216:217], v206 offset:0x5000
	ds_read_b64_tr_b16 v[218:219], v206 offset:0x5800
	ds_read_b64_tr_b16 v[220:221], v206 offset:0x6000
	ds_read_b64_tr_b16 v[222:223], v206 offset:0x6800
	ds_read_b64_tr_b16 v[224:225], v206 offset:0x7000
	ds_read_b64_tr_b16 v[226:227], v206 offset:0x7800
	v_permlane32_swap_b32_e32 v81, v83
	v_permlane32_swap_b32_e32 v84, v86
	v_permlane32_swap_b32_e32 v85, v87
	v_permlane32_swap_b32_e32 v88, v90
	v_permlane32_swap_b32_e32 v89, v91
	v_permlane32_swap_b32_e32 v92, v94
	s_waitcnt lgkmcnt(9)
	v_mfma_f32_32x32x16_bf16 v[64:79], v[146:149], v[134:137], v[64:79]
	v_permlane32_swap_b32_e32 v93, v95
	s_waitcnt lgkmcnt(8)
	v_mfma_f32_32x32x16_bf16 v[96:111], v[150:153], v[134:137], v[96:111]
	s_waitcnt vmcnt(0)
	ds_write_b128 v211, v[162:165]
	s_nop 0
	s_waitcnt lgkmcnt(7)
	v_mfma_f32_32x32x16_bf16 v[0:15], v[80:83], v[184:187], v[0:15]
	ds_read_b64_tr_b16 v[184:185], v206 offset:0x4200
	ds_read_b64_tr_b16 v[186:187], v206 offset:0x4a00
	v_add_co_u32_e32 v150, vcc, s21, v178
	s_nop 1
	v_addc_co_u32_e32 v151, vcc, -1, v179, vcc
	v_add_co_u32_e32 v154, vcc, s22, v178
	s_nop 1
	v_addc_co_u32_e32 v155, vcc, -1, v179, vcc
	s_waitcnt lgkmcnt(7)
	v_mfma_f32_32x32x16_bf16 v[0:15], v[84:87], v[216:219], v[0:15]
	ds_read_b64_tr_b16 v[216:217], v206 offset:0x5200
	ds_read_b64_tr_b16 v[218:219], v206 offset:0x5a00
	global_load_dwordx4 v[146:149], v[150:151], off
	s_nop 0
	global_load_dwordx4 v[150:153], v[150:151], off offset:-512
	s_nop 0
	global_load_dwordx4 v[158:161], v[154:155], off
	s_nop 0
	global_load_dwordx4 v[154:157], v[154:155], off offset:-512
	s_waitcnt lgkmcnt(7)
	v_mfma_f32_32x32x16_bf16 v[0:15], v[88:91], v[220:223], v[0:15]
	ds_read_b64_tr_b16 v[220:221], v206 offset:0x6200
	ds_read_b64_tr_b16 v[222:223], v206 offset:0x6a00
	v_exp_f32_e32 v200, v64
	v_exp_f32_e32 v240, v79
	s_waitcnt lgkmcnt(7)
	v_mfma_f32_32x32x16_bf16 v[0:15], v[92:95], v[224:227], v[0:15]
	ds_read_b64_tr_b16 v[224:225], v206 offset:0x7200
	ds_read_b64_tr_b16 v[226:227], v206 offset:0x7a00
	v_exp_f32_e32 v201, v65
	v_exp_f32_e32 v241, v76
	ds_write_b128 v212, v[174:177]
	s_waitcnt lgkmcnt(7)
	v_mfma_f32_32x32x16_bf16 v[16:31], v[80:83], v[184:187], v[16:31]
	ds_read_b64_tr_b16 v[184:185], v206 offset:0x4400
	ds_read_b64_tr_b16 v[186:187], v206 offset:0x4c00
	v_exp_f32_e32 v202, v66
	v_exp_f32_e32 v250, v77
	s_waitcnt lgkmcnt(7)
	v_mfma_f32_32x32x16_bf16 v[16:31], v[84:87], v[216:219], v[16:31]
	ds_read_b64_tr_b16 v[216:217], v206 offset:0x5400
	ds_read_b64_tr_b16 v[218:219], v206 offset:0x5c00
	v_exp_f32_e32 v203, v67
	s_waitcnt lgkmcnt(7)
	v_mfma_f32_32x32x16_bf16 v[16:31], v[88:91], v[220:223], v[16:31]
	ds_read_b64_tr_b16 v[220:221], v206 offset:0x6400
	ds_read_b64_tr_b16 v[222:223], v206 offset:0x6c00
	v_exp_f32_e32 v204, v78
	s_waitcnt lgkmcnt(7)
	v_mfma_f32_32x32x16_bf16 v[16:31], v[92:95], v[224:227], v[16:31]
	ds_read_b64_tr_b16 v[224:225], v206 offset:0x7400
	ds_read_b64_tr_b16 v[226:227], v206 offset:0x7c00
	v_exp_f32_e32 v205, v75
	ds_write_b128 v213, v[166:169]
	s_waitcnt lgkmcnt(7)
	v_mfma_f32_32x32x16_bf16 v[32:47], v[80:83], v[184:187], v[32:47]
	ds_read_b64_tr_b16 v[184:185], v206 offset:0x4600
	ds_read_b64_tr_b16 v[186:187], v206 offset:0x4e00
	v_exp_f32_e32 v215, v74
	v_exp_f32_e32 v188, v68
	s_waitcnt lgkmcnt(7)
	v_mfma_f32_32x32x16_bf16 v[32:47], v[84:87], v[216:219], v[32:47]
	ds_read_b64_tr_b16 v[216:217], v206 offset:0x5600
	ds_read_b64_tr_b16 v[218:219], v206 offset:0x5e00
	v_exp_f32_e32 v189, v69
	v_exp_f32_e32 v196, v70
	s_waitcnt lgkmcnt(7)
	v_mfma_f32_32x32x16_bf16 v[32:47], v[88:91], v[220:223], v[32:47]
	ds_read_b64_tr_b16 v[220:221], v206 offset:0x6600
	ds_read_b64_tr_b16 v[222:223], v206 offset:0x6e00
	v_exp_f32_e32 v197, v71
	v_exp_f32_e32 v198, v72
	s_waitcnt lgkmcnt(7)
	v_mfma_f32_32x32x16_bf16 v[32:47], v[92:95], v[224:227], v[32:47]
	ds_read_b64_tr_b16 v[224:225], v206 offset:0x7600
	ds_read_b64_tr_b16 v[226:227], v206 offset:0x7e00
	v_exp_f32_e32 v199, v73
	ds_write_b128 v214, v[170:173]
	s_waitcnt lgkmcnt(7)
	v_mfma_f32_32x32x16_bf16 v[48:63], v[80:83], v[184:187], v[48:63]
	s_waitcnt vmcnt(4)
	s_waitcnt lgkmcnt(5)
	v_mfma_f32_32x32x16_bf16 v[48:63], v[84:87], v[216:219], v[48:63]
	s_waitcnt lgkmcnt(3)
	v_mfma_f32_32x32x16_bf16 v[48:63], v[88:91], v[220:223], v[48:63]
	s_waitcnt lgkmcnt(0)
	s_barrier
; __device__ __forceinline__ void finishSM(f32x16& p0, f32x16& p1, float alpha, float& l_reg, bf16x8& pa0, bf16x8& pa1, bf16x8& pa2, bf16x8& pa3) {
;   for (int r = 0; r < 16; ++r) p1[r] = __builtin_amdgcn_exp2f(p1[r]);
;   float ps = 0; for (int r = 0; r < 16; ++r) ps += p0[r]; for (int r = 0; r < 16; ++r) ps += p1[r];
;   { auto rr = __builtin_amdgcn_permlane32_swap(__float_as_uint(ps), __float_as_uint(ps), false, false);
;     ps = __uint_as_float(rr[0]) + __uint_as_float(rr[1]); }
;   l_reg = l_reg * alpha + ps;
;     ...
;   PK4(p0, 0, pa0); PK4(p0, 8, pa1); PK4(p1, 0, pa2); PK4(p1, 8, pa3);
;     ...
; }
	v_mfma_f32_32x32x16_bf16 v[48:63], v[92:95], v[224:227], v[48:63]
	ds_read_b128 v[64:67], v207
	ds_read_b128 v[68:71], v207 offset:8192
	ds_read_b128 v[162:165], v208
	ds_read_b128 v[166:169], v208 offset:8192
	v_exp_f32_e32 v170, v104
	v_exp_f32_e32 v171, v105
	v_exp_f32_e32 v172, v106
	v_exp_f32_e32 v173, v107
	v_exp_f32_e32 v174, v108
	v_exp_f32_e32 v175, v109
	v_exp_f32_e32 v176, v110
	v_exp_f32_e32 v111, v111
	s_waitcnt lgkmcnt(3)
	v_mfma_f32_32x32x16_bf16 v[80:95], v[64:67], v[142:145], 0
	v_exp_f32_e32 v236, v96
	v_add_f32_e32 v96, 0, v200
	v_add_f32_e32 v96, v201, v96
	v_add_f32_e32 v96, v202, v96
	s_waitcnt lgkmcnt(2)
	v_mfma_f32_32x32x16_bf16 v[64:79], v[68:71], v[142:145], 0
	v_add_f32_e32 v96, v203, v96
	v_add_f32_e32 v96, v188, v96
	v_add_f32_e32 v96, v189, v96
	s_waitcnt lgkmcnt(1)
	v_mfma_f32_32x32x16_bf16 v[80:95], v[162:165], v[138:141], v[80:95]
	v_add_f32_e32 v96, v196, v96
	v_add_f32_e32 v96, v197, v96
	v_add_f32_e32 v96, v198, v96
	s_waitcnt lgkmcnt(0)
	v_mfma_f32_32x32x16_bf16 v[64:79], v[166:169], v[138:141], v[64:79]
	ds_read_b128 v[162:165], v209
	ds_read_b128 v[166:169], v209 offset:8192
	v_add_f32_e32 v96, v199, v96
	v_add_f32_e32 v96, v215, v96
	v_add_f32_e32 v96, v205, v96
	v_add_f32_e32 v96, v241, v96
	v_exp_f32_e32 v237, v97
	s_waitcnt lgkmcnt(1)
	v_mfma_f32_32x32x16_bf16 v[80:95], v[162:165], v[112:115], v[80:95]
	v_add_f32_e32 v96, v250, v96
	v_exp_f32_e32 v238, v98
	v_add_f32_e32 v96, v204, v96
	v_exp_f32_e32 v239, v99
	s_waitcnt lgkmcnt(0)
	v_mfma_f32_32x32x16_bf16 v[64:79], v[166:169], v[112:115], v[64:79]
	ds_read_b128 v[162:165], v210
	ds_read_b128 v[166:169], v210 offset:8192
	v_add_f32_e32 v96, v240, v96
	v_exp_f32_e32 v247, v100
	v_add_f32_e32 v96, v236, v96
	v_exp_f32_e32 v248, v101
	s_waitcnt lgkmcnt(1)
	v_mfma_f32_32x32x16_bf16 v[80:95], v[162:165], v[116:119], v[80:95]
	v_add_f32_e32 v96, v237, v96
	v_exp_f32_e32 v249, v102
	v_add_f32_e32 v96, v238, v96
	v_exp_f32_e32 v252, v103
	s_waitcnt lgkmcnt(0)
	v_mfma_f32_32x32x16_bf16 v[64:79], v[166:169], v[116:119], v[64:79]
	ds_read_b128 v[162:165], v190 offset:0
	ds_read_b128 v[166:169], v190 offset:8192
	v_add_f32_e32 v96, v239, v96
	v_add_f32_e32 v96, v247, v96
	v_add_f32_e32 v96, v248, v96
	v_add_f32_e32 v96, v249, v96
	v_add_f32_e32 v96, v252, v96
	v_add_f32_e32 v96, v170, v96
	s_waitcnt lgkmcnt(1)
	v_mfma_f32_32x32x16_bf16 v[80:95], v[162:165], v[120:123], v[80:95]
	v_add_f32_e32 v96, v171, v96
	v_add_f32_e32 v96, v172, v96
	v_add_f32_e32 v96, v173, v96
	v_add_f32_e32 v96, v174, v96
	v_add_f32_e32 v96, v175, v96
	s_waitcnt lgkmcnt(0)
	v_mfma_f32_32x32x16_bf16 v[64:79], v[166:169], v[120:123], v[64:79]
	ds_read_b128 v[162:165], v191 offset:0
	ds_read_b128 v[166:169], v191 offset:8192
	v_add_f32_e32 v96, v176, v96
	v_add_f32_e32 v181, v111, v96
	v_mov_b32_e32 v183, v181
	s_nop 1
	v_permlane32_swap_b32_e32 v181, v183
	v_pk_add_f32 v[96:97], v[180:181], v[182:183]
	s_waitcnt lgkmcnt(1)
	v_mfma_f32_32x32x16_bf16 v[80:95], v[162:165], v[124:127], v[80:95]
	s_nop 0
	v_add_f32_e32 v96, v128, v96
	v_add_f32_e32 v128, v96, v97
	v_cvt_pk_bf16_f32 v96, v200, v201
	v_cvt_pk_bf16_f32 v97, v202, v203
	s_waitcnt lgkmcnt(0)
	v_mfma_f32_32x32x16_bf16 v[64:79], v[166:169], v[124:127], v[64:79]
	ds_read_b128 v[162:165], v192 offset:0
	ds_read_b128 v[166:169], v192 offset:8192
	v_cvt_pk_bf16_f32 v98, v188, v189
	v_cvt_pk_bf16_f32 v99, v196, v197
	v_cvt_pk_bf16_f32 v100, v198, v199
	v_cvt_pk_bf16_f32 v101, v215, v205
	v_cvt_pk_bf16_f32 v102, v241, v250
	v_cvt_pk_bf16_f32 v103, v204, v240
	s_waitcnt lgkmcnt(1)
	v_mfma_f32_32x32x16_bf16 v[80:95], v[162:165], v[130:133], v[80:95]
	v_cvt_pk_bf16_f32 v104, v236, v237
	v_cvt_pk_bf16_f32 v105, v238, v239
	v_cvt_pk_bf16_f32 v106, v247, v248
	v_cvt_pk_bf16_f32 v107, v249, v252
	v_cvt_pk_bf16_f32 v108, v170, v171
	s_waitcnt lgkmcnt(0)
	v_mfma_f32_32x32x16_bf16 v[64:79], v[166:169], v[130:133], v[64:79]
	ds_read_b128 v[162:165], v193 offset:0
	ds_read_b128 v[166:169], v193 offset:8192
	ds_read_b64_tr_b16 v[180:181], v206 offset:0x8000
	ds_read_b64_tr_b16 v[182:183], v206 offset:0x8800
	ds_read_b64_tr_b16 v[184:185], v206 offset:0x9000
	ds_read_b64_tr_b16 v[186:187], v206 offset:0x9800
	ds_read_b64_tr_b16 v[216:217], v206 offset:0xa000
	ds_read_b64_tr_b16 v[218:219], v206 offset:0xa800
	ds_read_b64_tr_b16 v[220:221], v206 offset:0xb000
	ds_read_b64_tr_b16 v[222:223], v206 offset:0xb800
	v_cvt_pk_bf16_f32 v109, v172, v173
	v_cvt_pk_bf16_f32 v110, v174, v175
	v_cvt_pk_bf16_f32 v111, v176, v111
	s_nop 0
	v_permlane32_swap_b32_e32 v96, v98
	v_permlane32_swap_b32_e32 v97, v99
	s_waitcnt lgkmcnt(9)
	v_mfma_f32_32x32x16_bf16 v[80:95], v[162:165], v[134:137], v[80:95]
	v_permlane32_swap_b32_e32 v100, v102
	v_permlane32_swap_b32_e32 v101, v103
	v_permlane32_swap_b32_e32 v104, v106
	v_permlane32_swap_b32_e32 v105, v107
	v_permlane32_swap_b32_e32 v108, v110
	s_waitcnt lgkmcnt(8)
	v_mfma_f32_32x32x16_bf16 v[64:79], v[166:169], v[134:137], v[64:79]
	v_permlane32_swap_b32_e32 v109, v111
	s_waitcnt vmcnt(0)
	ds_write_b128 v211, v[146:149] offset:16384
	s_nop 0
	s_waitcnt lgkmcnt(7)
	v_mfma_f32_32x32x16_bf16 v[0:15], v[96:99], v[180:183], v[0:15]
	ds_read_b64_tr_b16 v[180:181], v206 offset:0x8200
	ds_read_b64_tr_b16 v[182:183], v206 offset:0x8a00
	v_add_co_u32_e32 v166, vcc, s23, v178
	s_nop 1
	v_addc_co_u32_e32 v167, vcc, -1, v179, vcc
	v_add_co_u32_e32 v170, vcc, s24, v178
	s_nop 1
	v_addc_co_u32_e32 v171, vcc, -1, v179, vcc
	s_waitcnt lgkmcnt(7)
; #define SBAR() __builtin_amdgcn_sched_barrier(0)
; template <int D0, int BOFF> __device__ __forceinline__ void pv_one_i(f32x16& od, int vb, bf16x8 pa0, bf16x8 pa1, bf16x8 pa2, bf16x8 pa3) {
;   const s16x4 l0 = tr_read<BOFF + v_rd_off(D0, 0, 0)>(vb), h0 = tr_read<BOFF + v_rd_off(D0, 0, 1)>(vb), l1 = tr_read<BOFF + v_rd_off(D0, 1, 0)>(vb), h1 = tr_read<BOFF + v_rd_off(D0, 1, 1)>(vb);
;   const s16x4 l2 = tr_read<BOFF + v_rd_off(D0, 2, 0)>(vb), h2 = tr_read<BOFF + v_rd_off(D0, 2, 1)>(vb), l3 = tr_read<BOFF + v_rd_off(D0, 3, 0)>(vb), h3 = tr_read<BOFF + v_rd_off(D0, 3, 1)>(vb);
;   asm volatile("s_waitcnt lgkmcnt(0)" ::: "memory"); SBAR();
;     ...
;   od = __builtin_amdgcn_mfma_f32_32x32x16_bf16(pa0, PK(l0, h0), od, 0, 0, 0);
;   od = __builtin_amdgcn_mfma_f32_32x32x16_bf16(pa1, PK(l1, h1), od, 0, 0, 0);
;   od = __builtin_amdgcn_mfma_f32_32x32x16_bf16(pa2, PK(l2, h2), od, 0, 0, 0);
;   od = __builtin_amdgcn_mfma_f32_32x32x16_bf16(pa3, PK(l3, h3), od, 0, 0, 0);
;     ...
; }
; template <int BOFF> __device__ __forceinline__ void pv_i(f32x16* o, int vb, bf16x8 pa0, bf16x8 pa1, bf16x8 pa2, bf16x8 pa3) {
;   pv_one_i<0, BOFF>(o[0], vb, pa0, pa1, pa2, pa3); pv_one_i<1, BOFF>(o[1], vb, pa0, pa1, pa2, pa3); pv_one_i<2, BOFF>(o[2], vb, pa0, pa1, pa2, pa3); pv_one_i<3, BOFF>(o[3], vb, pa0, pa1, pa2, pa3);
; }
	v_mfma_f32_32x32x16_bf16 v[0:15], v[100:103], v[184:187], v[0:15]
	ds_read_b64_tr_b16 v[184:185], v206 offset:0x9200
	ds_read_b64_tr_b16 v[186:187], v206 offset:0x9a00
	global_load_dwordx4 v[162:165], v[166:167], off
	s_nop 0
	global_load_dwordx4 v[166:169], v[166:167], off offset:-512
	s_nop 0
	global_load_dwordx4 v[174:177], v[170:171], off
	s_nop 0
	global_load_dwordx4 v[170:173], v[170:171], off offset:-512
	s_waitcnt lgkmcnt(7)
	v_mfma_f32_32x32x16_bf16 v[0:15], v[104:107], v[216:219], v[0:15]
	ds_read_b64_tr_b16 v[216:217], v206 offset:0xa200
	ds_read_b64_tr_b16 v[218:219], v206 offset:0xaa00
	v_exp_f32_e32 v200, v80
	v_exp_f32_e32 v240, v93
	s_waitcnt lgkmcnt(7)
	v_mfma_f32_32x32x16_bf16 v[0:15], v[108:111], v[220:223], v[0:15]
	ds_read_b64_tr_b16 v[220:221], v206 offset:0xb200
	ds_read_b64_tr_b16 v[222:223], v206 offset:0xba00
	v_exp_f32_e32 v201, v81
	v_exp_f32_e32 v241, v94
	ds_write_b128 v212, v[158:161] offset:16384
	s_waitcnt lgkmcnt(7)
	v_mfma_f32_32x32x16_bf16 v[16:31], v[96:99], v[180:183], v[16:31]
	ds_read_b64_tr_b16 v[180:181], v206 offset:0x8400
	ds_read_b64_tr_b16 v[182:183], v206 offset:0x8c00
	v_exp_f32_e32 v202, v82
	v_exp_f32_e32 v250, v95
	s_waitcnt lgkmcnt(7)
	v_mfma_f32_32x32x16_bf16 v[16:31], v[100:103], v[184:187], v[16:31]
	ds_read_b64_tr_b16 v[184:185], v206 offset:0x9400
	ds_read_b64_tr_b16 v[186:187], v206 offset:0x9c00
	v_exp_f32_e32 v203, v83
	s_waitcnt lgkmcnt(7)
	v_mfma_f32_32x32x16_bf16 v[16:31], v[104:107], v[216:219], v[16:31]
	ds_read_b64_tr_b16 v[216:217], v206 offset:0xa400
	ds_read_b64_tr_b16 v[218:219], v206 offset:0xac00
	v_exp_f32_e32 v204, v84
	s_waitcnt lgkmcnt(7)
	v_mfma_f32_32x32x16_bf16 v[16:31], v[108:111], v[220:223], v[16:31]
	ds_read_b64_tr_b16 v[220:221], v206 offset:0xb400
	ds_read_b64_tr_b16 v[222:223], v206 offset:0xbc00
	v_exp_f32_e32 v205, v85
	ds_write_b128 v213, v[150:153] offset:16384
	s_waitcnt lgkmcnt(7)
	v_mfma_f32_32x32x16_bf16 v[32:47], v[96:99], v[180:183], v[32:47]
	ds_read_b64_tr_b16 v[180:181], v206 offset:0x8600
	ds_read_b64_tr_b16 v[182:183], v206 offset:0x8e00
	v_exp_f32_e32 v215, v92
	v_exp_f32_e32 v188, v86
	s_waitcnt lgkmcnt(7)
	v_mfma_f32_32x32x16_bf16 v[32:47], v[100:103], v[184:187], v[32:47]
	ds_read_b64_tr_b16 v[184:185], v206 offset:0x9600
	ds_read_b64_tr_b16 v[186:187], v206 offset:0x9e00
	v_exp_f32_e32 v189, v87
	v_exp_f32_e32 v196, v88
	s_waitcnt lgkmcnt(7)
	v_mfma_f32_32x32x16_bf16 v[32:47], v[104:107], v[216:219], v[32:47]
	ds_read_b64_tr_b16 v[216:217], v206 offset:0xa600
	ds_read_b64_tr_b16 v[218:219], v206 offset:0xae00
	v_exp_f32_e32 v197, v89
	v_exp_f32_e32 v198, v90
	s_waitcnt lgkmcnt(7)
	v_mfma_f32_32x32x16_bf16 v[32:47], v[108:111], v[220:223], v[32:47]
	ds_read_b64_tr_b16 v[220:221], v206 offset:0xb600
	ds_read_b64_tr_b16 v[222:223], v206 offset:0xbe00
	v_exp_f32_e32 v199, v91
	ds_write_b128 v214, v[154:157] offset:16384
	s_waitcnt lgkmcnt(7)
	v_mfma_f32_32x32x16_bf16 v[48:63], v[96:99], v[180:183], v[48:63]
	s_waitcnt vmcnt(4)
	s_waitcnt lgkmcnt(5)
	v_mfma_f32_32x32x16_bf16 v[48:63], v[100:103], v[184:187], v[48:63]
	s_waitcnt lgkmcnt(3)
	v_mfma_f32_32x32x16_bf16 v[48:63], v[104:107], v[216:219], v[48:63]
	s_waitcnt lgkmcnt(0)
	s_barrier
	v_mfma_f32_32x32x16_bf16 v[48:63], v[108:111], v[220:223], v[48:63]
	ds_read_b128 v[80:83], v207 offset:16384
	ds_read_b128 v[96:99], v207 offset:24576
	ds_read_b128 v[146:149], v208 offset:16384
	ds_read_b128 v[150:153], v208 offset:24576
	v_exp_f32_e32 v154, v72
	v_exp_f32_e32 v155, v73
	v_exp_f32_e32 v156, v74
	v_exp_f32_e32 v157, v75
	v_exp_f32_e32 v158, v76
	v_exp_f32_e32 v159, v77
	v_exp_f32_e32 v160, v78
	v_exp_f32_e32 v79, v79
	s_waitcnt lgkmcnt(3)
	v_mfma_f32_32x32x16_bf16 v[80:95], v[80:83], v[142:145], 0
	v_exp_f32_e32 v236, v64
	v_add_f32_e32 v64, 0, v200
	v_add_f32_e32 v64, v201, v64
	v_add_f32_e32 v64, v202, v64
	s_waitcnt lgkmcnt(2)
	v_mfma_f32_32x32x16_bf16 v[96:111], v[96:99], v[142:145], 0
	v_add_f32_e32 v64, v203, v64
	v_add_f32_e32 v64, v204, v64
	v_add_f32_e32 v64, v205, v64
	s_waitcnt lgkmcnt(1)
	v_mfma_f32_32x32x16_bf16 v[80:95], v[146:149], v[138:141], v[80:95]
	v_add_f32_e32 v64, v188, v64
	v_add_f32_e32 v64, v189, v64
	v_add_f32_e32 v64, v196, v64
	s_waitcnt lgkmcnt(0)
	v_mfma_f32_32x32x16_bf16 v[96:111], v[150:153], v[138:141], v[96:111]
	ds_read_b128 v[146:149], v209 offset:16384
	ds_read_b128 v[150:153], v209 offset:24576
	v_add_f32_e32 v64, v197, v64
	v_add_f32_e32 v64, v198, v64
	v_add_f32_e32 v64, v199, v64
	v_add_f32_e32 v64, v215, v64
	v_exp_f32_e32 v237, v65
	s_waitcnt lgkmcnt(1)
	v_mfma_f32_32x32x16_bf16 v[80:95], v[146:149], v[112:115], v[80:95]
	v_add_f32_e32 v64, v240, v64
	v_exp_f32_e32 v238, v66
	v_add_f32_e32 v64, v241, v64
	v_exp_f32_e32 v239, v67
	s_waitcnt lgkmcnt(0)
	v_mfma_f32_32x32x16_bf16 v[96:111], v[150:153], v[112:115], v[96:111]
	ds_read_b128 v[146:149], v210 offset:16384
	ds_read_b128 v[150:153], v210 offset:24576
	v_add_f32_e32 v64, v250, v64
	v_exp_f32_e32 v247, v68
	v_add_f32_e32 v64, v236, v64
	v_exp_f32_e32 v248, v69
	s_waitcnt lgkmcnt(1)
	v_mfma_f32_32x32x16_bf16 v[80:95], v[146:149], v[116:119], v[80:95]
	v_add_f32_e32 v64, v237, v64
	v_exp_f32_e32 v249, v70
	v_add_f32_e32 v64, v238, v64
	v_exp_f32_e32 v252, v71
	s_waitcnt lgkmcnt(0)
	v_mfma_f32_32x32x16_bf16 v[96:111], v[150:153], v[116:119], v[96:111]
	ds_read_b128 v[146:149], v190 offset:16384
	ds_read_b128 v[150:153], v190 offset:24576
	v_add_f32_e32 v64, v239, v64
	v_add_f32_e32 v64, v247, v64
	v_add_f32_e32 v64, v248, v64
	v_add_f32_e32 v64, v249, v64
	v_add_f32_e32 v64, v252, v64
	v_add_f32_e32 v64, v154, v64
	s_waitcnt lgkmcnt(1)
; #define SBAR() __builtin_amdgcn_sched_barrier(0)
; __device__ __forceinline__ void finishSM(f32x16& p0, f32x16& p1, float alpha, float& l_reg, bf16x8& pa0, bf16x8& pa1, bf16x8& pa2, bf16x8& pa3) {
;   for (int r = 0; r < 16; ++r) p1[r] = __builtin_amdgcn_exp2f(p1[r]);
;   float ps = 0; for (int r = 0; r < 16; ++r) ps += p0[r]; for (int r = 0; r < 16; ++r) ps += p1[r];
;   { auto rr = __builtin_amdgcn_permlane32_swap(__float_as_uint(ps), __float_as_uint(ps), false, false);
;     ps = __uint_as_float(rr[0]) + __uint_as_float(rr[1]); }
;   l_reg = l_reg * alpha + ps;
;     ...
;   PK4(p0, 0, pa0); PK4(p0, 8, pa1); PK4(p1, 0, pa2); PK4(p1, 8, pa3);
;     ...
; }
; template <int D0, int BOFF> __device__ __forceinline__ void pv_one_i(f32x16& od, int vb, bf16x8 pa0, bf16x8 pa1, bf16x8 pa2, bf16x8 pa3) {
;   const s16x4 l0 = tr_read<BOFF + v_rd_off(D0, 0, 0)>(vb), h0 = tr_read<BOFF + v_rd_off(D0, 0, 1)>(vb), l1 = tr_read<BOFF + v_rd_off(D0, 1, 0)>(vb), h1 = tr_read<BOFF + v_rd_off(D0, 1, 1)>(vb);
;   const s16x4 l2 = tr_read<BOFF + v_rd_off(D0, 2, 0)>(vb), h2 = tr_read<BOFF + v_rd_off(D0, 2, 1)>(vb), l3 = tr_read<BOFF + v_rd_off(D0, 3, 0)>(vb), h3 = tr_read<BOFF + v_rd_off(D0, 3, 1)>(vb);
;   asm volatile("s_waitcnt lgkmcnt(0)" ::: "memory"); SBAR();
;     ...
;   od = __builtin_amdgcn_mfma_f32_32x32x16_bf16(pa0, PK(l0, h0), od, 0, 0, 0);
;   od = __builtin_amdgcn_mfma_f32_32x32x16_bf16(pa1, PK(l1, h1), od, 0, 0, 0);
;   od = __builtin_amdgcn_mfma_f32_32x32x16_bf16(pa2, PK(l2, h2), od, 0, 0, 0);
;   od = __builtin_amdgcn_mfma_f32_32x32x16_bf16(pa3, PK(l3, h3), od, 0, 0, 0);
;     ...
; }
; template <int BOFF> __device__ __forceinline__ void pv_i(f32x16* o, int vb, bf16x8 pa0, bf16x8 pa1, bf16x8 pa2, bf16x8 pa3) {
;   pv_one_i<0, BOFF>(o[0], vb, pa0, pa1, pa2, pa3); pv_one_i<1, BOFF>(o[1], vb, pa0, pa1, pa2, pa3); pv_one_i<2, BOFF>(o[2], vb, pa0, pa1, pa2, pa3); pv_one_i<3, BOFF>(o[3], vb, pa0, pa1, pa2, pa3);
; }
	v_mfma_f32_32x32x16_bf16 v[80:95], v[146:149], v[120:123], v[80:95]
	v_add_f32_e32 v64, v155, v64
	v_add_f32_e32 v64, v156, v64
	v_add_f32_e32 v64, v157, v64
	v_add_f32_e32 v64, v158, v64
	v_add_f32_e32 v64, v159, v64
	s_waitcnt lgkmcnt(0)
	v_mfma_f32_32x32x16_bf16 v[96:111], v[150:153], v[120:123], v[96:111]
	ds_read_b128 v[146:149], v191 offset:16384
	ds_read_b128 v[150:153], v191 offset:24576
	v_add_f32_e32 v64, v160, v64
	v_add_f32_e32 v180, v79, v64
	v_cvt_pk_bf16_f32 v64, v200, v201
	v_cvt_pk_bf16_f32 v65, v202, v203
	v_cvt_pk_bf16_f32 v66, v204, v205
	v_cvt_pk_bf16_f32 v67, v188, v189
	s_waitcnt lgkmcnt(1)
	v_mfma_f32_32x32x16_bf16 v[80:95], v[146:149], v[124:127], v[80:95]
	v_cvt_pk_bf16_f32 v68, v196, v197
	v_cvt_pk_bf16_f32 v69, v198, v199
	v_cvt_pk_bf16_f32 v70, v215, v240
	v_cvt_pk_bf16_f32 v71, v241, v250
	v_cvt_pk_bf16_f32 v72, v236, v237
	s_waitcnt lgkmcnt(0)
	v_mfma_f32_32x32x16_bf16 v[96:111], v[150:153], v[124:127], v[96:111]
	ds_read_b128 v[146:149], v192 offset:16384
	ds_read_b128 v[150:153], v192 offset:24576
	v_cvt_pk_bf16_f32 v73, v238, v239
	v_cvt_pk_bf16_f32 v74, v247, v248
	v_cvt_pk_bf16_f32 v75, v249, v252
	v_cvt_pk_bf16_f32 v76, v154, v155
	v_cvt_pk_bf16_f32 v77, v156, v157
	v_cvt_pk_bf16_f32 v78, v158, v159
	s_waitcnt lgkmcnt(1)
	v_mfma_f32_32x32x16_bf16 v[80:95], v[146:149], v[130:133], v[80:95]
	v_cvt_pk_bf16_f32 v79, v160, v79
	v_mov_b32_e32 v182, v180
	v_permlane32_swap_b32_e32 v64, v66
	v_permlane32_swap_b32_e32 v65, v67
	v_permlane32_swap_b32_e32 v68, v70
	s_waitcnt lgkmcnt(0)
	v_mfma_f32_32x32x16_bf16 v[96:111], v[150:153], v[130:133], v[96:111]
	ds_read_b128 v[146:149], v193 offset:16384
	ds_read_b128 v[150:153], v193 offset:24576
	ds_read_b64_tr_b16 v[184:185], v206 offset:0
	ds_read_b64_tr_b16 v[186:187], v206 offset:0x800
	ds_read_b64_tr_b16 v[216:217], v206 offset:0x1000
	ds_read_b64_tr_b16 v[218:219], v206 offset:0x1800
	ds_read_b64_tr_b16 v[220:221], v206 offset:0x2000
	ds_read_b64_tr_b16 v[222:223], v206 offset:0x2800
	ds_read_b64_tr_b16 v[224:225], v206 offset:0x3000
	ds_read_b64_tr_b16 v[226:227], v206 offset:0x3800
	v_permlane32_swap_b32_e32 v69, v71
	v_permlane32_swap_b32_e32 v72, v74
	v_permlane32_swap_b32_e32 v73, v75
	v_permlane32_swap_b32_e32 v76, v78
	v_permlane32_swap_b32_e32 v77, v79
	v_permlane32_swap_b32_e32 v180, v182
	s_waitcnt lgkmcnt(9)
	v_mfma_f32_32x32x16_bf16 v[80:95], v[146:149], v[134:137], v[80:95]
	s_waitcnt lgkmcnt(8)
	v_mfma_f32_32x32x16_bf16 v[96:111], v[150:153], v[134:137], v[96:111]
	s_waitcnt vmcnt(0)
	ds_write_b128 v211, v[162:165] offset:32768
	s_nop 0
	s_waitcnt lgkmcnt(7)
	v_mfma_f32_32x32x16_bf16 v[0:15], v[64:67], v[184:187], v[0:15]
	ds_read_b64_tr_b16 v[184:185], v206 offset:0x200
	ds_read_b64_tr_b16 v[186:187], v206 offset:0xa00
	v_add_co_u32_e32 v150, vcc, s25, v178
	s_nop 1
	v_addc_co_u32_e32 v151, vcc, -1, v179, vcc
	v_add_co_u32_e32 v154, vcc, s45, v178
	s_nop 1
	v_addc_co_u32_e32 v155, vcc, -1, v179, vcc
	s_waitcnt lgkmcnt(7)
	v_mfma_f32_32x32x16_bf16 v[0:15], v[68:71], v[216:219], v[0:15]
	ds_read_b64_tr_b16 v[216:217], v206 offset:0x1200
	ds_read_b64_tr_b16 v[218:219], v206 offset:0x1a00
	global_load_dwordx4 v[146:149], v[150:151], off
	s_nop 0
	global_load_dwordx4 v[150:153], v[150:151], off offset:-512
	s_nop 0
	global_load_dwordx4 v[158:161], v[154:155], off
	s_nop 0
	global_load_dwordx4 v[154:157], v[154:155], off offset:-512
	s_waitcnt lgkmcnt(7)
	v_mfma_f32_32x32x16_bf16 v[0:15], v[72:75], v[220:223], v[0:15]
	ds_read_b64_tr_b16 v[220:221], v206 offset:0x2200
	ds_read_b64_tr_b16 v[222:223], v206 offset:0x2a00
	v_exp_f32_e32 v200, v80
	v_exp_f32_e32 v240, v95
	s_waitcnt lgkmcnt(7)
	v_mfma_f32_32x32x16_bf16 v[0:15], v[76:79], v[224:227], v[0:15]
	ds_read_b64_tr_b16 v[224:225], v206 offset:0x3200
	ds_read_b64_tr_b16 v[226:227], v206 offset:0x3a00
	v_exp_f32_e32 v201, v81
	v_exp_f32_e32 v241, v92
	ds_write_b128 v212, v[174:177] offset:32768
	s_waitcnt lgkmcnt(7)
	v_mfma_f32_32x32x16_bf16 v[16:31], v[64:67], v[184:187], v[16:31]
	ds_read_b64_tr_b16 v[184:185], v206 offset:0x400
	ds_read_b64_tr_b16 v[186:187], v206 offset:0xc00
	v_exp_f32_e32 v202, v82
	v_exp_f32_e32 v250, v93
	s_waitcnt lgkmcnt(7)
	v_mfma_f32_32x32x16_bf16 v[16:31], v[68:71], v[216:219], v[16:31]
	ds_read_b64_tr_b16 v[216:217], v206 offset:0x1400
	ds_read_b64_tr_b16 v[218:219], v206 offset:0x1c00
	v_exp_f32_e32 v203, v83
	s_waitcnt lgkmcnt(7)
	v_mfma_f32_32x32x16_bf16 v[16:31], v[72:75], v[220:223], v[16:31]
	ds_read_b64_tr_b16 v[220:221], v206 offset:0x2400
	ds_read_b64_tr_b16 v[222:223], v206 offset:0x2c00
	v_exp_f32_e32 v204, v94
	s_waitcnt lgkmcnt(7)
	v_mfma_f32_32x32x16_bf16 v[16:31], v[76:79], v[224:227], v[16:31]
	ds_read_b64_tr_b16 v[224:225], v206 offset:0x3400
	ds_read_b64_tr_b16 v[226:227], v206 offset:0x3c00
	v_exp_f32_e32 v205, v91
	ds_write_b128 v213, v[166:169] offset:32768
	s_waitcnt lgkmcnt(7)
	v_mfma_f32_32x32x16_bf16 v[32:47], v[64:67], v[184:187], v[32:47]
	ds_read_b64_tr_b16 v[184:185], v206 offset:0x600
	ds_read_b64_tr_b16 v[186:187], v206 offset:0xe00
	v_exp_f32_e32 v215, v90
	v_exp_f32_e32 v188, v84
	s_waitcnt lgkmcnt(7)
	v_mfma_f32_32x32x16_bf16 v[32:47], v[68:71], v[216:219], v[32:47]
	ds_read_b64_tr_b16 v[216:217], v206 offset:0x1600
	ds_read_b64_tr_b16 v[218:219], v206 offset:0x1e00
	v_exp_f32_e32 v189, v85
	v_exp_f32_e32 v196, v86
	s_waitcnt lgkmcnt(7)
	v_mfma_f32_32x32x16_bf16 v[32:47], v[72:75], v[220:223], v[32:47]
	ds_read_b64_tr_b16 v[220:221], v206 offset:0x2600
	ds_read_b64_tr_b16 v[222:223], v206 offset:0x2e00
	v_exp_f32_e32 v197, v87
	v_exp_f32_e32 v198, v88
	s_waitcnt lgkmcnt(7)
	v_mfma_f32_32x32x16_bf16 v[32:47], v[76:79], v[224:227], v[32:47]
	ds_read_b64_tr_b16 v[224:225], v206 offset:0x3600
	ds_read_b64_tr_b16 v[226:227], v206 offset:0x3e00
	v_exp_f32_e32 v199, v89
	ds_write_b128 v214, v[170:173] offset:32768
	s_waitcnt lgkmcnt(7)
	v_mfma_f32_32x32x16_bf16 v[48:63], v[64:67], v[184:187], v[48:63]
	s_waitcnt vmcnt(4)
	s_waitcnt lgkmcnt(5)
	v_mfma_f32_32x32x16_bf16 v[48:63], v[68:71], v[216:219], v[48:63]
	s_waitcnt lgkmcnt(3)
	v_mfma_f32_32x32x16_bf16 v[48:63], v[72:75], v[220:223], v[48:63]
	s_waitcnt lgkmcnt(0)
	s_barrier
; __device__ __forceinline__ void finishSM(f32x16& p0, f32x16& p1, float alpha, float& l_reg, bf16x8& pa0, bf16x8& pa1, bf16x8& pa2, bf16x8& pa3) {
;   for (int r = 0; r < 16; ++r) p1[r] = __builtin_amdgcn_exp2f(p1[r]);
;   float ps = 0; for (int r = 0; r < 16; ++r) ps += p0[r]; for (int r = 0; r < 16; ++r) ps += p1[r];
;   { auto rr = __builtin_amdgcn_permlane32_swap(__float_as_uint(ps), __float_as_uint(ps), false, false);
;     ps = __uint_as_float(rr[0]) + __uint_as_float(rr[1]); }
;   l_reg = l_reg * alpha + ps;
;     ...
;   PK4(p0, 0, pa0); PK4(p0, 8, pa1); PK4(p1, 0, pa2); PK4(p1, 8, pa3);
;     ...
; }
	v_mfma_f32_32x32x16_bf16 v[48:63], v[76:79], v[224:227], v[48:63]
	ds_read_b128 v[64:67], v207 offset:32768
	ds_read_b128 v[80:83], v207 offset:40960
	ds_read_b128 v[162:165], v208 offset:32768
	ds_read_b128 v[166:169], v208 offset:40960
	v_exp_f32_e32 v170, v104
	v_exp_f32_e32 v171, v105
	v_exp_f32_e32 v172, v106
	v_exp_f32_e32 v173, v107
	v_exp_f32_e32 v174, v108
	v_exp_f32_e32 v175, v109
	v_exp_f32_e32 v176, v110
	v_exp_f32_e32 v111, v111
	s_waitcnt lgkmcnt(3)
	v_mfma_f32_32x32x16_bf16 v[64:79], v[64:67], v[142:145], 0
	v_exp_f32_e32 v236, v96
	v_add_f32_e32 v96, 0, v200
	v_add_f32_e32 v96, v201, v96
	v_add_f32_e32 v96, v202, v96
	s_waitcnt lgkmcnt(2)
	v_mfma_f32_32x32x16_bf16 v[80:95], v[80:83], v[142:145], 0
	v_add_f32_e32 v96, v203, v96
	v_add_f32_e32 v96, v188, v96
	v_add_f32_e32 v96, v189, v96
	s_waitcnt lgkmcnt(1)
	v_mfma_f32_32x32x16_bf16 v[64:79], v[162:165], v[138:141], v[64:79]
	v_add_f32_e32 v96, v196, v96
	v_add_f32_e32 v96, v197, v96
	v_add_f32_e32 v96, v198, v96
	s_waitcnt lgkmcnt(0)
	v_mfma_f32_32x32x16_bf16 v[80:95], v[166:169], v[138:141], v[80:95]
	ds_read_b128 v[162:165], v209 offset:32768
	ds_read_b128 v[166:169], v209 offset:40960
	v_add_f32_e32 v96, v199, v96
	v_add_f32_e32 v96, v215, v96
	v_add_f32_e32 v96, v205, v96
	v_add_f32_e32 v96, v241, v96
	v_exp_f32_e32 v237, v97
	s_waitcnt lgkmcnt(1)
	v_mfma_f32_32x32x16_bf16 v[64:79], v[162:165], v[112:115], v[64:79]
	v_add_f32_e32 v96, v250, v96
	v_exp_f32_e32 v238, v98
	v_add_f32_e32 v96, v204, v96
	v_exp_f32_e32 v239, v99
	s_waitcnt lgkmcnt(0)
	v_mfma_f32_32x32x16_bf16 v[80:95], v[166:169], v[112:115], v[80:95]
	ds_read_b128 v[162:165], v210 offset:32768
	ds_read_b128 v[166:169], v210 offset:40960
	v_add_f32_e32 v96, v240, v96
	v_exp_f32_e32 v247, v100
	v_add_f32_e32 v96, v236, v96
	v_exp_f32_e32 v248, v101
	s_waitcnt lgkmcnt(1)
	v_mfma_f32_32x32x16_bf16 v[64:79], v[162:165], v[116:119], v[64:79]
	v_add_f32_e32 v96, v237, v96
	v_exp_f32_e32 v249, v102
	v_add_f32_e32 v96, v238, v96
	v_exp_f32_e32 v252, v103
	s_waitcnt lgkmcnt(0)
	v_mfma_f32_32x32x16_bf16 v[80:95], v[166:169], v[116:119], v[80:95]
	ds_read_b128 v[162:165], v190 offset:32768
	ds_read_b128 v[166:169], v190 offset:40960
	v_add_f32_e32 v96, v239, v96
	v_add_f32_e32 v96, v247, v96
	v_add_f32_e32 v96, v248, v96
	v_add_f32_e32 v96, v249, v96
	v_add_f32_e32 v96, v252, v96
	v_add_f32_e32 v96, v170, v96
	s_waitcnt lgkmcnt(1)
	v_mfma_f32_32x32x16_bf16 v[64:79], v[162:165], v[120:123], v[64:79]
	v_add_f32_e32 v96, v171, v96
	v_add_f32_e32 v96, v172, v96
	v_add_f32_e32 v96, v173, v96
	v_add_f32_e32 v96, v174, v96
	v_add_f32_e32 v96, v175, v96
	s_waitcnt lgkmcnt(0)
	v_mfma_f32_32x32x16_bf16 v[80:95], v[166:169], v[120:123], v[80:95]
	ds_read_b128 v[162:165], v191 offset:32768
	ds_read_b128 v[166:169], v191 offset:40960
	v_add_f32_e32 v96, v176, v96
	v_add_f32_e32 v181, v111, v96
	v_mov_b32_e32 v183, v181
	s_nop 1
	v_permlane32_swap_b32_e32 v181, v183
	v_pk_add_f32 v[96:97], v[180:181], v[182:183]
	s_waitcnt lgkmcnt(1)
	v_mfma_f32_32x32x16_bf16 v[64:79], v[162:165], v[124:127], v[64:79]
	s_nop 0
	v_add_f32_e32 v96, v128, v96
	v_add_f32_e32 v128, v96, v97
	v_cvt_pk_bf16_f32 v96, v200, v201
	v_cvt_pk_bf16_f32 v97, v202, v203
	s_waitcnt lgkmcnt(0)
	v_mfma_f32_32x32x16_bf16 v[80:95], v[166:169], v[124:127], v[80:95]
	ds_read_b128 v[162:165], v192 offset:32768
	ds_read_b128 v[166:169], v192 offset:40960
	v_cvt_pk_bf16_f32 v98, v188, v189
	v_cvt_pk_bf16_f32 v99, v196, v197
	v_cvt_pk_bf16_f32 v100, v198, v199
	v_cvt_pk_bf16_f32 v101, v215, v205
	v_cvt_pk_bf16_f32 v102, v241, v250
	v_cvt_pk_bf16_f32 v103, v204, v240
	s_waitcnt lgkmcnt(1)
	v_mfma_f32_32x32x16_bf16 v[64:79], v[162:165], v[130:133], v[64:79]
	v_cvt_pk_bf16_f32 v104, v236, v237
	v_cvt_pk_bf16_f32 v105, v238, v239
	v_cvt_pk_bf16_f32 v106, v247, v248
	v_cvt_pk_bf16_f32 v107, v249, v252
	v_cvt_pk_bf16_f32 v108, v170, v171
	s_waitcnt lgkmcnt(0)
	v_mfma_f32_32x32x16_bf16 v[80:95], v[166:169], v[130:133], v[80:95]
	ds_read_b128 v[162:165], v193 offset:32768
	ds_read_b128 v[166:169], v193 offset:40960
	ds_read_b64_tr_b16 v[180:181], v206 offset:0x4000
	ds_read_b64_tr_b16 v[182:183], v206 offset:0x4800
	ds_read_b64_tr_b16 v[184:185], v206 offset:0x5000
	ds_read_b64_tr_b16 v[186:187], v206 offset:0x5800
	ds_read_b64_tr_b16 v[216:217], v206 offset:0x6000
	ds_read_b64_tr_b16 v[218:219], v206 offset:0x6800
	ds_read_b64_tr_b16 v[220:221], v206 offset:0x7000
	ds_read_b64_tr_b16 v[222:223], v206 offset:0x7800
	v_cvt_pk_bf16_f32 v109, v172, v173
	v_cvt_pk_bf16_f32 v110, v174, v175
	v_cvt_pk_bf16_f32 v111, v176, v111
	s_nop 0
	v_permlane32_swap_b32_e32 v96, v98
	v_permlane32_swap_b32_e32 v97, v99
	s_waitcnt lgkmcnt(9)
	v_mfma_f32_32x32x16_bf16 v[64:79], v[162:165], v[134:137], v[64:79]
	v_permlane32_swap_b32_e32 v100, v102
	v_permlane32_swap_b32_e32 v101, v103
	v_permlane32_swap_b32_e32 v104, v106
	v_permlane32_swap_b32_e32 v105, v107
	v_permlane32_swap_b32_e32 v108, v110
	s_waitcnt lgkmcnt(8)
	v_mfma_f32_32x32x16_bf16 v[80:95], v[166:169], v[134:137], v[80:95]
	v_permlane32_swap_b32_e32 v109, v111
	s_waitcnt vmcnt(0)
	ds_write_b128 v211, v[146:149]
	s_nop 0
	s_waitcnt lgkmcnt(7)
	v_mfma_f32_32x32x16_bf16 v[0:15], v[96:99], v[180:183], v[0:15]
	ds_read_b64_tr_b16 v[180:181], v206 offset:0x4200
	ds_read_b64_tr_b16 v[182:183], v206 offset:0x4a00
	v_add_co_u32_e32 v166, vcc, s52, v178
	s_nop 1
	v_addc_co_u32_e32 v167, vcc, -1, v179, vcc
	v_add_co_u32_e32 v170, vcc, s53, v178
	s_nop 1
	v_addc_co_u32_e32 v171, vcc, -1, v179, vcc
	s_waitcnt lgkmcnt(7)
; #define SBAR() __builtin_amdgcn_sched_barrier(0)
; template <int D0, int BOFF> __device__ __forceinline__ void pv_one_i(f32x16& od, int vb, bf16x8 pa0, bf16x8 pa1, bf16x8 pa2, bf16x8 pa3) {
;   const s16x4 l0 = tr_read<BOFF + v_rd_off(D0, 0, 0)>(vb), h0 = tr_read<BOFF + v_rd_off(D0, 0, 1)>(vb), l1 = tr_read<BOFF + v_rd_off(D0, 1, 0)>(vb), h1 = tr_read<BOFF + v_rd_off(D0, 1, 1)>(vb);
;   const s16x4 l2 = tr_read<BOFF + v_rd_off(D0, 2, 0)>(vb), h2 = tr_read<BOFF + v_rd_off(D0, 2, 1)>(vb), l3 = tr_read<BOFF + v_rd_off(D0, 3, 0)>(vb), h3 = tr_read<BOFF + v_rd_off(D0, 3, 1)>(vb);
;   asm volatile("s_waitcnt lgkmcnt(0)" ::: "memory"); SBAR();
;     ...
;   od = __builtin_amdgcn_mfma_f32_32x32x16_bf16(pa0, PK(l0, h0), od, 0, 0, 0);
;   od = __builtin_amdgcn_mfma_f32_32x32x16_bf16(pa1, PK(l1, h1), od, 0, 0, 0);
;   od = __builtin_amdgcn_mfma_f32_32x32x16_bf16(pa2, PK(l2, h2), od, 0, 0, 0);
;   od = __builtin_amdgcn_mfma_f32_32x32x16_bf16(pa3, PK(l3, h3), od, 0, 0, 0);
;     ...
; }
; template <int BOFF> __device__ __forceinline__ void pv_i(f32x16* o, int vb, bf16x8 pa0, bf16x8 pa1, bf16x8 pa2, bf16x8 pa3) {
;   pv_one_i<0, BOFF>(o[0], vb, pa0, pa1, pa2, pa3); pv_one_i<1, BOFF>(o[1], vb, pa0, pa1, pa2, pa3); pv_one_i<2, BOFF>(o[2], vb, pa0, pa1, pa2, pa3); pv_one_i<3, BOFF>(o[3], vb, pa0, pa1, pa2, pa3);
; }
	v_mfma_f32_32x32x16_bf16 v[0:15], v[100:103], v[184:187], v[0:15]
	ds_read_b64_tr_b16 v[184:185], v206 offset:0x5200
	ds_read_b64_tr_b16 v[186:187], v206 offset:0x5a00
	global_load_dwordx4 v[162:165], v[166:167], off
	s_nop 0
	global_load_dwordx4 v[166:169], v[166:167], off offset:-512
	s_nop 0
	global_load_dwordx4 v[174:177], v[170:171], off
	s_nop 0
	global_load_dwordx4 v[170:173], v[170:171], off offset:-512
	s_waitcnt lgkmcnt(7)
	v_mfma_f32_32x32x16_bf16 v[0:15], v[104:107], v[216:219], v[0:15]
	ds_read_b64_tr_b16 v[216:217], v206 offset:0x6200
	ds_read_b64_tr_b16 v[218:219], v206 offset:0x6a00
	v_exp_f32_e32 v200, v64
	v_exp_f32_e32 v240, v70
	s_waitcnt lgkmcnt(7)
	v_mfma_f32_32x32x16_bf16 v[0:15], v[108:111], v[220:223], v[0:15]
	ds_read_b64_tr_b16 v[220:221], v206 offset:0x7200
	ds_read_b64_tr_b16 v[222:223], v206 offset:0x7a00
	v_exp_f32_e32 v201, v65
	v_exp_f32_e32 v241, v71
	ds_write_b128 v212, v[158:161]
	s_waitcnt lgkmcnt(7)
	v_mfma_f32_32x32x16_bf16 v[16:31], v[96:99], v[180:183], v[16:31]
	ds_read_b64_tr_b16 v[180:181], v206 offset:0x4400
	ds_read_b64_tr_b16 v[182:183], v206 offset:0x4c00
	v_exp_f32_e32 v202, v66
	v_exp_f32_e32 v250, v78
	s_waitcnt lgkmcnt(7)
	v_mfma_f32_32x32x16_bf16 v[16:31], v[100:103], v[184:187], v[16:31]
	ds_read_b64_tr_b16 v[184:185], v206 offset:0x5400
	ds_read_b64_tr_b16 v[186:187], v206 offset:0x5c00
	v_exp_f32_e32 v203, v67
	v_exp_f32_e32 v251, v79
	s_waitcnt lgkmcnt(7)
	v_mfma_f32_32x32x16_bf16 v[16:31], v[104:107], v[216:219], v[16:31]
	ds_read_b64_tr_b16 v[216:217], v206 offset:0x6400
	ds_read_b64_tr_b16 v[218:219], v206 offset:0x6c00
	v_exp_f32_e32 v204, v68
	s_waitcnt lgkmcnt(7)
	v_mfma_f32_32x32x16_bf16 v[16:31], v[108:111], v[220:223], v[16:31]
	ds_read_b64_tr_b16 v[220:221], v206 offset:0x7400
	ds_read_b64_tr_b16 v[222:223], v206 offset:0x7c00
	v_exp_f32_e32 v205, v69
	ds_write_b128 v213, v[150:153]
	s_waitcnt lgkmcnt(7)
	v_mfma_f32_32x32x16_bf16 v[32:47], v[96:99], v[180:183], v[32:47]
	ds_read_b64_tr_b16 v[180:181], v206 offset:0x4600
	ds_read_b64_tr_b16 v[182:183], v206 offset:0x4e00
	v_exp_f32_e32 v188, v72
	v_exp_f32_e32 v189, v73
	s_waitcnt lgkmcnt(7)
	v_mfma_f32_32x32x16_bf16 v[32:47], v[100:103], v[184:187], v[32:47]
	ds_read_b64_tr_b16 v[184:185], v206 offset:0x5600
	ds_read_b64_tr_b16 v[186:187], v206 offset:0x5e00
	v_exp_f32_e32 v196, v74
	v_exp_f32_e32 v197, v75
	s_waitcnt lgkmcnt(7)
	v_mfma_f32_32x32x16_bf16 v[32:47], v[104:107], v[216:219], v[32:47]
	ds_read_b64_tr_b16 v[216:217], v206 offset:0x6600
	ds_read_b64_tr_b16 v[218:219], v206 offset:0x6e00
	v_exp_f32_e32 v198, v76
	v_exp_f32_e32 v199, v77
	s_waitcnt lgkmcnt(7)
	v_mfma_f32_32x32x16_bf16 v[32:47], v[108:111], v[220:223], v[32:47]
	ds_read_b64_tr_b16 v[220:221], v206 offset:0x7600
	ds_read_b64_tr_b16 v[222:223], v206 offset:0x7e00
	ds_write_b128 v214, v[154:157]
	s_waitcnt lgkmcnt(7)
	v_mfma_f32_32x32x16_bf16 v[48:63], v[96:99], v[180:183], v[48:63]
	s_waitcnt vmcnt(4)
	s_waitcnt lgkmcnt(5)
	v_mfma_f32_32x32x16_bf16 v[48:63], v[100:103], v[184:187], v[48:63]
	s_waitcnt lgkmcnt(3)
	v_mfma_f32_32x32x16_bf16 v[48:63], v[104:107], v[216:219], v[48:63]
	s_waitcnt lgkmcnt(0)
	s_barrier
	v_mfma_f32_32x32x16_bf16 v[48:63], v[108:111], v[220:223], v[48:63]
	ds_read_b128 v[64:67], v207
	ds_read_b128 v[68:71], v207 offset:8192
	ds_read_b128 v[146:149], v208
	ds_read_b128 v[150:153], v208 offset:8192
	v_exp_f32_e32 v154, v88
	v_exp_f32_e32 v155, v89
	v_exp_f32_e32 v156, v90
	v_exp_f32_e32 v157, v91
	v_exp_f32_e32 v158, v92
	v_exp_f32_e32 v159, v93
	v_exp_f32_e32 v160, v94
	v_exp_f32_e32 v95, v95
	s_waitcnt lgkmcnt(3)
	v_mfma_f32_32x32x16_bf16 v[96:111], v[64:67], v[142:145], 0
	v_exp_f32_e32 v236, v80
	v_add_f32_e32 v80, 0, v200
	v_add_f32_e32 v80, v201, v80
	v_add_f32_e32 v80, v202, v80
	s_waitcnt lgkmcnt(2)
	v_mfma_f32_32x32x16_bf16 v[64:79], v[68:71], v[142:145], 0
	v_add_f32_e32 v80, v203, v80
	v_add_f32_e32 v80, v204, v80
	v_add_f32_e32 v80, v205, v80
	s_waitcnt lgkmcnt(1)
	v_mfma_f32_32x32x16_bf16 v[96:111], v[146:149], v[138:141], v[96:111]
	v_add_f32_e32 v80, v240, v80
	v_add_f32_e32 v80, v241, v80
	v_add_f32_e32 v80, v188, v80
	s_waitcnt lgkmcnt(0)
	v_mfma_f32_32x32x16_bf16 v[64:79], v[150:153], v[138:141], v[64:79]
	ds_read_b128 v[146:149], v209
	ds_read_b128 v[150:153], v209 offset:8192
	v_add_f32_e32 v80, v189, v80
	v_add_f32_e32 v80, v196, v80
	v_add_f32_e32 v80, v197, v80
	v_add_f32_e32 v80, v198, v80
	v_exp_f32_e32 v237, v81
	s_waitcnt lgkmcnt(1)
	v_mfma_f32_32x32x16_bf16 v[96:111], v[146:149], v[112:115], v[96:111]
	v_add_f32_e32 v80, v199, v80
	v_exp_f32_e32 v238, v82
	v_add_f32_e32 v80, v250, v80
	v_exp_f32_e32 v239, v83
	s_waitcnt lgkmcnt(0)
	v_mfma_f32_32x32x16_bf16 v[64:79], v[150:153], v[112:115], v[64:79]
	ds_read_b128 v[146:149], v210
	ds_read_b128 v[150:153], v210 offset:8192
	v_add_f32_e32 v80, v251, v80
	v_exp_f32_e32 v247, v84
	v_add_f32_e32 v80, v236, v80
	v_exp_f32_e32 v248, v85
	s_waitcnt lgkmcnt(1)
	v_mfma_f32_32x32x16_bf16 v[96:111], v[146:149], v[116:119], v[96:111]
	v_add_f32_e32 v80, v237, v80
	v_exp_f32_e32 v249, v86
	v_add_f32_e32 v80, v238, v80
	v_exp_f32_e32 v252, v87
	s_waitcnt lgkmcnt(0)
	v_mfma_f32_32x32x16_bf16 v[64:79], v[150:153], v[116:119], v[64:79]
	ds_read_b128 v[146:149], v190 offset:0
	ds_read_b128 v[150:153], v190 offset:8192
	v_add_f32_e32 v80, v239, v80
	v_add_f32_e32 v80, v247, v80
	v_add_f32_e32 v80, v248, v80
	v_add_f32_e32 v80, v249, v80
	v_add_f32_e32 v80, v252, v80
	v_add_f32_e32 v80, v154, v80
	s_waitcnt lgkmcnt(1)
	v_mfma_f32_32x32x16_bf16 v[96:111], v[146:149], v[120:123], v[96:111]
	v_add_f32_e32 v80, v155, v80
	v_add_f32_e32 v80, v156, v80
	v_add_f32_e32 v80, v157, v80
	v_add_f32_e32 v80, v158, v80
	v_add_f32_e32 v80, v159, v80
	s_waitcnt lgkmcnt(0)
; #define SBAR() __builtin_amdgcn_sched_barrier(0)
; #define SLOAD(i, k0) do { sr_[i].vs0 = ld8(&Vh[(long)((k0) + sr) * LDK + sc]); sr_[i].vs1 = ld8(&Vh[(long)((k0) + 32 + sr) * LDK + sc]); \
;     sr_[i].ks0 = ld8(&Kh[(long)((k0) + sr) * LDK + sc]); sr_[i].ks1 = ld8(&Kh[(long)((k0) + 32 + sr) * LDK + sc]); } while (0)
; #define SWAIT() asm volatile("s_waitcnt vmcnt(4)" ::: "memory")
; #define NOP_() do { } while (0)
; template <int D0, int BOFF> __device__ __forceinline__ void pv_one_i(f32x16& od, int vb, bf16x8 pa0, bf16x8 pa1, bf16x8 pa2, bf16x8 pa3) {
;   const s16x4 l0 = tr_read<BOFF + v_rd_off(D0, 0, 0)>(vb), h0 = tr_read<BOFF + v_rd_off(D0, 0, 1)>(vb), l1 = tr_read<BOFF + v_rd_off(D0, 1, 0)>(vb), h1 = tr_read<BOFF + v_rd_off(D0, 1, 1)>(vb);
;   const s16x4 l2 = tr_read<BOFF + v_rd_off(D0, 2, 0)>(vb), h2 = tr_read<BOFF + v_rd_off(D0, 2, 1)>(vb), l3 = tr_read<BOFF + v_rd_off(D0, 3, 0)>(vb), h3 = tr_read<BOFF + v_rd_off(D0, 3, 1)>(vb);
;   asm volatile("s_waitcnt lgkmcnt(0)" ::: "memory"); SBAR();
;     ...
;   od = __builtin_amdgcn_mfma_f32_32x32x16_bf16(pa0, PK(l0, h0), od, 0, 0, 0);
;   od = __builtin_amdgcn_mfma_f32_32x32x16_bf16(pa1, PK(l1, h1), od, 0, 0, 0);
;   od = __builtin_amdgcn_mfma_f32_32x32x16_bf16(pa2, PK(l2, h2), od, 0, 0, 0);
;   od = __builtin_amdgcn_mfma_f32_32x32x16_bf16(pa3, PK(l3, h3), od, 0, 0, 0);
;     ...
; }
; template <int BOFF> __device__ __forceinline__ void pv_i(f32x16* o, int vb, bf16x8 pa0, bf16x8 pa1, bf16x8 pa2, bf16x8 pa3) {
;   pv_one_i<0, BOFF>(o[0], vb, pa0, pa1, pa2, pa3); pv_one_i<1, BOFF>(o[1], vb, pa0, pa1, pa2, pa3); pv_one_i<2, BOFF>(o[2], vb, pa0, pa1, pa2, pa3); pv_one_i<3, BOFF>(o[3], vb, pa0, pa1, pa2, pa3);
; }
; template <bool PARTIAL, bool FIXED> ...
;     ...
;   for (; j + 6 < NT; j += 6) {
;     HALF_B(1, 0, SLOAD(1, (j + 2) * KVBLK), do { SWAIT(); SWRITE_I(2, 0); } while (0));
;     HALF_A(2, 1, NOP_(), SLOAD(0, (j + 3) * KVBLK), do { SWAIT(); SWRITE_I(0, 1); } while (0));
;     HALF_B(0, 2, SLOAD(1, (j + 4) * KVBLK), do { SWAIT(); SWRITE_I(1, 0); } while (0));
;     HALF_A(1, 0, NOP_(), SLOAD(0, (j + 5) * KVBLK), do { SWAIT(); SWRITE_I(2, 1); } while (0));
;     HALF_B(2, 1, SLOAD(1, (j + 6) * KVBLK), do { SWAIT(); SWRITE_I(0, 0); } while (0));
;     HALF_A(0, 2, NOP_(), SLOAD(0, (j + 7) * KVBLK), do { SWAIT(); SWRITE_I(1, 1); } while (0));
	v_mfma_f32_32x32x16_bf16 v[64:79], v[150:153], v[120:123], v[64:79]
	ds_read_b128 v[146:149], v191 offset:0
	ds_read_b128 v[150:153], v191 offset:8192
	v_add_f32_e32 v80, v160, v80
	v_add_f32_e32 v80, v95, v80
	v_mov_b32_e32 v81, v80
	s_nop 1
	v_permlane32_swap_b32_e32 v80, v81
	v_add_f32_e32 v80, v80, v81
	s_waitcnt lgkmcnt(1)
	v_mfma_f32_32x32x16_bf16 v[96:111], v[146:149], v[124:127], v[96:111]
	v_add_f32_e32 v215, v128, v80
	v_cvt_pk_bf16_f32 v80, v200, v201
	v_cvt_pk_bf16_f32 v81, v202, v203
	v_cvt_pk_bf16_f32 v82, v204, v205
	v_cvt_pk_bf16_f32 v83, v240, v241
	s_waitcnt lgkmcnt(0)
	v_mfma_f32_32x32x16_bf16 v[64:79], v[150:153], v[124:127], v[64:79]
	ds_read_b128 v[146:149], v192 offset:0
	ds_read_b128 v[150:153], v192 offset:8192
	v_cvt_pk_bf16_f32 v84, v188, v189
	v_cvt_pk_bf16_f32 v85, v196, v197
	v_cvt_pk_bf16_f32 v86, v198, v199
	v_cvt_pk_bf16_f32 v87, v250, v251
	v_cvt_pk_bf16_f32 v88, v236, v237
	v_cvt_pk_bf16_f32 v89, v238, v239
	s_waitcnt lgkmcnt(1)
	v_mfma_f32_32x32x16_bf16 v[96:111], v[146:149], v[130:133], v[96:111]
	v_cvt_pk_bf16_f32 v90, v247, v248
	v_cvt_pk_bf16_f32 v91, v249, v252
	v_cvt_pk_bf16_f32 v92, v154, v155
	v_cvt_pk_bf16_f32 v93, v156, v157
	v_cvt_pk_bf16_f32 v94, v158, v159
	s_waitcnt lgkmcnt(0)
	v_mfma_f32_32x32x16_bf16 v[64:79], v[150:153], v[130:133], v[64:79]
	ds_read_b128 v[146:149], v193 offset:0
	ds_read_b128 v[150:153], v193 offset:8192
	ds_read_b64_tr_b16 v[180:181], v206 offset:0x8000
	ds_read_b64_tr_b16 v[182:183], v206 offset:0x8800
	ds_read_b64_tr_b16 v[184:185], v206 offset:0x9000
	ds_read_b64_tr_b16 v[186:187], v206 offset:0x9800
	ds_read_b64_tr_b16 v[216:217], v206 offset:0xa000
	ds_read_b64_tr_b16 v[218:219], v206 offset:0xa800
	ds_read_b64_tr_b16 v[220:221], v206 offset:0xb000
	ds_read_b64_tr_b16 v[222:223], v206 offset:0xb800
	v_cvt_pk_bf16_f32 v95, v160, v95
	s_nop 0
	v_permlane32_swap_b32_e32 v80, v82
	v_permlane32_swap_b32_e32 v81, v83
	v_permlane32_swap_b32_e32 v84, v86
	v_permlane32_swap_b32_e32 v85, v87
	s_waitcnt lgkmcnt(9)
	v_mfma_f32_32x32x16_bf16 v[96:111], v[146:149], v[134:137], v[96:111]
	v_permlane32_swap_b32_e32 v88, v90
	v_permlane32_swap_b32_e32 v89, v91
	v_permlane32_swap_b32_e32 v92, v94
	v_permlane32_swap_b32_e32 v93, v95
	s_waitcnt lgkmcnt(8)
	v_mfma_f32_32x32x16_bf16 v[64:79], v[150:153], v[134:137], v[64:79]
	s_waitcnt vmcnt(0)
	ds_write_b128 v211, v[162:165] offset:16384
	s_nop 0
	s_waitcnt lgkmcnt(7)
	v_mfma_f32_32x32x16_bf16 v[0:15], v[80:83], v[180:183], v[0:15]
	ds_read_b64_tr_b16 v[180:181], v206 offset:0x8200
	ds_read_b64_tr_b16 v[182:183], v206 offset:0x8a00
	v_add_co_u32_e32 v150, vcc, s58, v178
	s_nop 1
	v_addc_co_u32_e32 v151, vcc, -1, v179, vcc
	s_waitcnt lgkmcnt(7)
	v_mfma_f32_32x32x16_bf16 v[0:15], v[84:87], v[184:187], v[0:15]
	ds_read_b64_tr_b16 v[184:185], v206 offset:0x9200
	ds_read_b64_tr_b16 v[186:187], v206 offset:0x9a00
	global_load_dwordx4 v[146:149], v[150:151], off
	global_load_dwordx4 v[154:157], v[150:151], off offset:-512
	s_nop 0
	global_load_dwordx4 v[150:153], v[178:179], off
	global_load_dwordx4 v[158:161], v[178:179], off offset:-512
	s_waitcnt lgkmcnt(7)
	v_mfma_f32_32x32x16_bf16 v[0:15], v[88:91], v[216:219], v[0:15]
	ds_read_b64_tr_b16 v[216:217], v206 offset:0xa200
	ds_read_b64_tr_b16 v[218:219], v206 offset:0xaa00
	s_waitcnt lgkmcnt(7)
	v_mfma_f32_32x32x16_bf16 v[0:15], v[92:95], v[220:223], v[0:15]
	ds_read_b64_tr_b16 v[220:221], v206 offset:0xb200
	ds_read_b64_tr_b16 v[222:223], v206 offset:0xba00
	ds_write_b128 v212, v[174:177] offset:16384
	s_waitcnt lgkmcnt(7)
	v_mfma_f32_32x32x16_bf16 v[16:31], v[80:83], v[180:183], v[16:31]
	ds_read_b64_tr_b16 v[180:181], v206 offset:0x8400
	ds_read_b64_tr_b16 v[182:183], v206 offset:0x8c00
	s_waitcnt lgkmcnt(7)
	v_mfma_f32_32x32x16_bf16 v[16:31], v[84:87], v[184:187], v[16:31]
	ds_read_b64_tr_b16 v[184:185], v206 offset:0x9400
	ds_read_b64_tr_b16 v[186:187], v206 offset:0x9c00
	s_waitcnt lgkmcnt(7)
	v_mfma_f32_32x32x16_bf16 v[16:31], v[88:91], v[216:219], v[16:31]
	ds_read_b64_tr_b16 v[216:217], v206 offset:0xa400
	ds_read_b64_tr_b16 v[218:219], v206 offset:0xac00
	s_waitcnt lgkmcnt(7)
	v_mfma_f32_32x32x16_bf16 v[16:31], v[92:95], v[220:223], v[16:31]
	ds_read_b64_tr_b16 v[220:221], v206 offset:0xb400
	ds_read_b64_tr_b16 v[222:223], v206 offset:0xbc00
	ds_write_b128 v213, v[166:169] offset:16384
	s_waitcnt lgkmcnt(7)
	v_mfma_f32_32x32x16_bf16 v[32:47], v[80:83], v[180:183], v[32:47]
	ds_read_b64_tr_b16 v[180:181], v206 offset:0x8600
	ds_read_b64_tr_b16 v[182:183], v206 offset:0x8e00
	v_exp_f32_e32 v229, v96
	v_exp_f32_e32 v243, v97
	s_waitcnt lgkmcnt(7)
	v_mfma_f32_32x32x16_bf16 v[32:47], v[84:87], v[184:187], v[32:47]
	ds_read_b64_tr_b16 v[184:185], v206 offset:0x9600
	ds_read_b64_tr_b16 v[186:187], v206 offset:0x9e00
	v_exp_f32_e32 v244, v98
	v_exp_f32_e32 v246, v99
	s_waitcnt lgkmcnt(7)
	v_mfma_f32_32x32x16_bf16 v[32:47], v[88:91], v[216:219], v[32:47]
	ds_read_b64_tr_b16 v[216:217], v206 offset:0xa600
	ds_read_b64_tr_b16 v[218:219], v206 offset:0xae00
	v_exp_f32_e32 v242, v100
	v_exp_f32_e32 v245, v101
	s_waitcnt lgkmcnt(7)
	v_mfma_f32_32x32x16_bf16 v[32:47], v[92:95], v[220:223], v[32:47]
	ds_read_b64_tr_b16 v[220:221], v206 offset:0xb600
	ds_read_b64_tr_b16 v[222:223], v206 offset:0xbe00
	v_exp_f32_e32 v227, v102
	v_exp_f32_e32 v228, v103
	ds_write_b128 v214, v[170:173] offset:16384
	s_waitcnt lgkmcnt(7)
	v_mfma_f32_32x32x16_bf16 v[48:63], v[80:83], v[180:183], v[48:63]
	s_waitcnt lgkmcnt(5)
	v_mfma_f32_32x32x16_bf16 v[48:63], v[84:87], v[184:187], v[48:63]
	v_exp_f32_e32 v226, v105
	v_exp_f32_e32 v224, v106
	v_exp_f32_e32 v225, v107
	s_waitcnt vmcnt(4)
	s_add_i32 s28, s28, 6
	v_lshl_add_u64 v[178:179], v[178:179], 0, s[60:61]
	s_waitcnt lgkmcnt(3)
	v_mfma_f32_32x32x16_bf16 v[48:63], v[88:91], v[216:219], v[48:63]
	v_exp_f32_e32 v219, v110
	s_cmpk_lt_u32 s28, 0x75
	s_waitcnt lgkmcnt(1)
	v_mfma_f32_32x32x16_bf16 v[48:63], v[92:95], v[220:223], v[48:63]
	v_exp_f32_e32 v223, v104
	v_exp_f32_e32 v220, v108
	v_exp_f32_e32 v222, v109
	v_exp_f32_e32 v221, v111
	s_cbranch_scc1 .LBB0_352
; #define SWRITE_I(B, i) do { LDSV(wv0 + (B) * 16384) = sr_[i].vs0; LDSV(wv1 + (B) * 16384) = sr_[i].vs1; LDSV(wk0 + (B) * 16384) = sr_[i].ks0; LDSV(wk1 + (B) * 16384) = sr_[i].ks1; } while (0)
; #define NOP_() do { } while (0)
; template <bool PARTIAL, bool FIXED> ...
;     ...
;   if constexpr (!PARTIAL) { const int i1 = tid & 255;
;     warm0 = *(const unsigned*)(Qb_n + (long)(tid >> 1) * LDQ + (tid & 1) * 64);
;     warm1 = *(const unsigned*)((tid < 256 ? Kh_n : Vh_n) + (long)(i1 >> 1) * LDK + (i1 & 1) * 64); }
;   HALF_B(1, 0, NOP_(), SWRITE_I(2, 0));
	v_mov_b64_e32 v[200:201], 0x1600
	v_mov_b64_e32 v[202:203], 0x420
	v_mov_b64_e32 v[204:205], 0x41f
	v_mov_b64_e32 v[240:241], 0x1615
	v_mov_b64_e32 v[250:251], 0x400
	v_mov_b32_e32 v252, 0x7fc00000
	v_readlane_b32 s8, v255, 42
	v_readlane_b32 s9, v255, 43
	s_add_u32 s2, s8, s6
	s_addc_u32 s3, s9, s7
	s_lshl_b32 s4, s65, 1
	s_add_u32 s2, s2, s4
	s_addc_u32 s3, s3, 0
	v_ashrrev_i32_e32 v82, 1, v195
	v_mov_b64_e32 v[80:81], s[2:3]
	v_mad_i64_i32 v[80:81], s[2:3], v82, s17, v[80:81]
	v_lshlrev_b32_e32 v82, 7, v195
	v_and_b32_e32 v128, 0x80, v82
	v_lshl_add_u64 v[80:81], v[80:81], 0, v[128:129]
	s_add_u32 s4, s8, s64
	global_load_dword v216, v[80:81], off
	v_cmp_gt_i32_e32 vcc, s14, v195
	v_mov_b32_e32 v80, 0xa00
	v_mov_b32_e32 v81, 0x800
	s_addc_u32 s5, s9, s57
	v_cndmask_b32_e32 v80, v80, v81, vcc
	v_mov_b32_e32 v81, v129
	v_bfe_u32 v82, v195, 1, 7
	v_lshl_add_u64 v[80:81], s[4:5], 0, v[80:81]
	s_lshl_b32 s46, s56, 1
	v_mul_u32_u24_e32 v82, 0x600, v82
	v_lshl_add_u64 v[80:81], v[80:81], 0, s[46:47]
	v_lshlrev_b32_e32 v82, 1, v82
	v_mov_b32_e32 v83, v129
	v_lshl_add_u64 v[80:81], v[80:81], 0, v[82:83]
	v_lshl_add_u64 v[80:81], v[80:81], 0, v[128:129]
	global_load_dword v217, v[80:81], off
	v_and_b32_e32 v247, 0x3fffffc0, v195
	s_waitcnt lgkmcnt(0)
	s_barrier
	ds_read_b128 v[80:83], v207 offset:16384
	ds_read_b128 v[96:99], v207 offset:24576
	ds_read_b128 v[100:103], v208 offset:16384
	ds_read_b128 v[170:173], v208 offset:24576
	v_exp_f32_e32 v104, v68
	v_exp_f32_e32 v105, v69
	s_waitcnt lgkmcnt(3)
	v_mfma_f32_32x32x16_bf16 v[80:95], v[80:83], v[142:145], 0
	v_exp_f32_e32 v106, v70
	v_exp_f32_e32 v107, v71
	v_exp_f32_e32 v108, v72
	v_exp_f32_e32 v109, v73
	v_exp_f32_e32 v110, v74
	v_exp_f32_e32 v111, v75
	v_exp_f32_e32 v196, v76
	s_waitcnt lgkmcnt(1)
	v_mfma_f32_32x32x16_bf16 v[80:95], v[100:103], v[138:141], v[80:95]
	ds_read_b128 v[100:103], v209 offset:16384
	ds_read_b128 v[162:165], v209 offset:24576
	v_exp_f32_e32 v197, v77
	v_exp_f32_e32 v198, v78
	v_exp_f32_e32 v79, v79
	s_waitcnt lgkmcnt(1)
	v_mfma_f32_32x32x16_bf16 v[80:95], v[100:103], v[112:115], v[80:95]
	ds_read_b128 v[100:103], v210 offset:16384
	ds_read_b128 v[166:169], v210 offset:24576
	s_waitcnt lgkmcnt(1)
	v_mfma_f32_32x32x16_bf16 v[80:95], v[100:103], v[116:119], v[80:95]
	ds_read_b128 v[100:103], v190 offset:16384
	ds_read_b128 v[174:177], v190 offset:24576
	s_waitcnt lgkmcnt(1)
	v_mfma_f32_32x32x16_bf16 v[80:95], v[100:103], v[120:123], v[80:95]
	ds_read_b128 v[100:103], v191 offset:16384
	ds_read_b128 v[178:181], v191 offset:24576
	s_waitcnt lgkmcnt(1)
	v_mfma_f32_32x32x16_bf16 v[80:95], v[100:103], v[124:127], v[80:95]
	ds_read_b128 v[100:103], v192 offset:16384
	ds_read_b128 v[182:185], v192 offset:24576
	s_waitcnt lgkmcnt(1)
	v_mfma_f32_32x32x16_bf16 v[80:95], v[100:103], v[130:133], v[80:95]
	ds_read_b128 v[100:103], v193 offset:16384
	ds_read_b128 v[186:189], v193 offset:24576
	s_waitcnt lgkmcnt(1)
	v_mfma_f32_32x32x16_bf16 v[80:95], v[100:103], v[134:137], v[80:95]
	v_exp_f32_e32 v100, v64
	v_add_f32_e32 v64, 0, v229
	v_add_f32_e32 v64, v243, v64
	v_add_f32_e32 v64, v244, v64
	v_add_f32_e32 v64, v246, v64
	v_add_f32_e32 v64, v242, v64
	v_add_f32_e32 v64, v245, v64
	v_add_f32_e32 v64, v227, v64
	v_add_f32_e32 v64, v228, v64
	v_add_f32_e32 v64, v223, v64
	v_add_f32_e32 v64, v226, v64
	v_add_f32_e32 v64, v224, v64
	v_add_f32_e32 v64, v225, v64
	v_add_f32_e32 v64, v220, v64
	v_exp_f32_e32 v101, v65
	v_add_f32_e32 v64, v222, v64
	v_exp_f32_e32 v102, v66
	v_add_f32_e32 v64, v219, v64
	v_exp_f32_e32 v103, v67
	v_add_f32_e32 v64, v221, v64
	v_add_f32_e32 v64, v100, v64
	v_add_f32_e32 v64, v101, v64
	v_add_f32_e32 v64, v102, v64
	v_add_f32_e32 v64, v103, v64
	v_add_f32_e32 v64, v104, v64
	v_add_f32_e32 v64, v105, v64
	v_add_f32_e32 v64, v106, v64
	v_add_f32_e32 v64, v107, v64
	v_add_f32_e32 v64, v108, v64
	v_add_f32_e32 v64, v109, v64
	v_add_f32_e32 v64, v110, v64
	v_add_f32_e32 v64, v111, v64
	v_add_f32_e32 v64, v196, v64
	v_add_f32_e32 v64, v197, v64
	v_add_f32_e32 v64, v198, v64
	v_add_f32_e32 v128, v79, v64
	v_mov_b32_e32 v218, v128
	s_nop 1
	v_permlane32_swap_b32_e32 v128, v218
	v_cvt_pk_bf16_f32 v64, v229, v243
	v_cvt_pk_bf16_f32 v65, v244, v246
	v_cvt_pk_bf16_f32 v66, v242, v245
	v_cvt_pk_bf16_f32 v67, v227, v228
	v_cvt_pk_bf16_f32 v68, v223, v226
	v_cvt_pk_bf16_f32 v69, v224, v225
	v_cvt_pk_bf16_f32 v70, v220, v222
	v_cvt_pk_bf16_f32 v71, v219, v221
	v_cvt_pk_bf16_f32 v72, v100, v101
	v_cvt_pk_bf16_f32 v73, v102, v103
	v_cvt_pk_bf16_f32 v74, v104, v105
	v_cvt_pk_bf16_f32 v75, v106, v107
	v_cvt_pk_bf16_f32 v76, v108, v109
	v_cvt_pk_bf16_f32 v77, v110, v111
	v_cvt_pk_bf16_f32 v78, v196, v197
	v_cvt_pk_bf16_f32 v79, v198, v79
	s_nop 0
	v_permlane32_swap_b32_e32 v64, v66
	v_permlane32_swap_b32_e32 v65, v67
	v_permlane32_swap_b32_e32 v68, v70
	v_permlane32_swap_b32_e32 v69, v71
	v_permlane32_swap_b32_e32 v72, v74
	v_permlane32_swap_b32_e32 v73, v75
	v_permlane32_swap_b32_e32 v76, v78
	v_permlane32_swap_b32_e32 v77, v79
	ds_read_b64_tr_b16 v[100:101], v206 offset:0
	ds_read_b64_tr_b16 v[102:103], v206 offset:0x800
	ds_read_b64_tr_b16 v[104:105], v206 offset:0x1000
	ds_read_b64_tr_b16 v[106:107], v206 offset:0x1800
	ds_read_b64_tr_b16 v[108:109], v206 offset:0x2000
	ds_read_b64_tr_b16 v[110:111], v206 offset:0x2800
	ds_read_b64_tr_b16 v[220:221], v206 offset:0x3000
	ds_read_b64_tr_b16 v[222:223], v206 offset:0x3800
	s_waitcnt lgkmcnt(0)
	s_nop 0
	v_mfma_f32_32x32x16_bf16 v[0:15], v[64:67], v[100:103], v[0:15]
	ds_read_b64_tr_b16 v[100:101], v206 offset:0x200
	ds_read_b64_tr_b16 v[102:103], v206 offset:0xa00
	v_mfma_f32_32x32x16_bf16 v[0:15], v[68:71], v[104:107], v[0:15]
	ds_read_b64_tr_b16 v[104:105], v206 offset:0x1200
	ds_read_b64_tr_b16 v[106:107], v206 offset:0x1a00
	v_mfma_f32_32x32x16_bf16 v[0:15], v[72:75], v[108:111], v[0:15]
	ds_read_b64_tr_b16 v[108:109], v206 offset:0x2200
	ds_read_b64_tr_b16 v[110:111], v206 offset:0x2a00
	v_mfma_f32_32x32x16_bf16 v[0:15], v[76:79], v[220:223], v[0:15]
	ds_read_b64_tr_b16 v[220:221], v206 offset:0x3200
	ds_read_b64_tr_b16 v[222:223], v206 offset:0x3a00
	s_waitcnt lgkmcnt(0)
	v_mfma_f32_32x32x16_bf16 v[16:31], v[64:67], v[100:103], v[16:31]
	ds_read_b64_tr_b16 v[100:101], v206 offset:0x400
	ds_read_b64_tr_b16 v[102:103], v206 offset:0xc00
	v_mfma_f32_32x32x16_bf16 v[16:31], v[68:71], v[104:107], v[16:31]
	ds_read_b64_tr_b16 v[104:105], v206 offset:0x1400
	ds_read_b64_tr_b16 v[106:107], v206 offset:0x1c00
	v_mfma_f32_32x32x16_bf16 v[16:31], v[72:75], v[108:111], v[16:31]
	ds_read_b64_tr_b16 v[108:109], v206 offset:0x2400
	ds_read_b64_tr_b16 v[110:111], v206 offset:0x2c00
	v_mfma_f32_32x32x16_bf16 v[16:31], v[76:79], v[220:223], v[16:31]
	ds_read_b64_tr_b16 v[220:221], v206 offset:0x3400
	ds_read_b64_tr_b16 v[222:223], v206 offset:0x3c00
	s_waitcnt lgkmcnt(0)
	v_mfma_f32_32x32x16_bf16 v[32:47], v[64:67], v[100:103], v[32:47]
	ds_read_b64_tr_b16 v[100:101], v206 offset:0x600
	ds_read_b64_tr_b16 v[102:103], v206 offset:0xe00
	v_mfma_f32_32x32x16_bf16 v[32:47], v[68:71], v[104:107], v[32:47]
	ds_read_b64_tr_b16 v[104:105], v206 offset:0x1600
	ds_read_b64_tr_b16 v[106:107], v206 offset:0x1e00
	v_mfma_f32_32x32x16_bf16 v[32:47], v[72:75], v[108:111], v[32:47]
	ds_read_b64_tr_b16 v[108:109], v206 offset:0x2600
	ds_read_b64_tr_b16 v[110:111], v206 offset:0x2e00
	v_mfma_f32_32x32x16_bf16 v[32:47], v[76:79], v[220:223], v[32:47]
	ds_read_b64_tr_b16 v[220:221], v206 offset:0x3600
	ds_read_b64_tr_b16 v[222:223], v206 offset:0x3e00
	s_waitcnt lgkmcnt(0)
	v_mfma_f32_32x32x16_bf16 v[48:63], v[64:67], v[100:103], v[48:63]
	s_waitcnt vmcnt(5)
	ds_write_b128 v211, v[146:149] offset:32768
	s_waitcnt vmcnt(3)
	ds_write_b128 v212, v[150:153] offset:32768
	ds_write_b128 v213, v[154:157] offset:32768
	s_waitcnt vmcnt(2)
	ds_write_b128 v214, v[158:161] offset:32768
	s_waitcnt lgkmcnt(0)
	s_barrier
	v_mfma_f32_32x32x16_bf16 v[48:63], v[68:71], v[104:107], v[48:63]
	v_mfma_f32_32x32x16_bf16 v[48:63], v[72:75], v[108:111], v[48:63]
	v_mfma_f32_32x32x16_bf16 v[48:63], v[76:79], v[220:223], v[48:63]
	ds_read_b128 v[64:67], v207 offset:32768
	ds_read_b128 v[100:103], v208 offset:32768
	s_add_i32 s2, 0, 0x18000
	s_waitcnt lgkmcnt(1)
	v_mfma_f32_32x32x16_bf16 v[64:79], v[64:67], v[142:145], 0
	s_waitcnt lgkmcnt(0)
	v_mfma_f32_32x32x16_bf16 v[64:79], v[100:103], v[138:141], v[64:79]
	ds_read_b128 v[100:103], v209 offset:32768
	s_waitcnt lgkmcnt(0)
	v_mfma_f32_32x32x16_bf16 v[64:79], v[100:103], v[112:115], v[64:79]
	ds_read_b128 v[100:103], v210 offset:32768
	s_waitcnt lgkmcnt(0)
	v_mfma_f32_32x32x16_bf16 v[64:79], v[100:103], v[116:119], v[64:79]
	ds_read_b128 v[100:103], v190 offset:32768
	s_waitcnt lgkmcnt(0)
	v_mfma_f32_32x32x16_bf16 v[64:79], v[100:103], v[120:123], v[64:79]
	ds_read_b128 v[100:103], v191 offset:32768
	s_waitcnt lgkmcnt(0)
	v_mfma_f32_32x32x16_bf16 v[64:79], v[100:103], v[124:127], v[64:79]
	ds_read_b128 v[100:103], v192 offset:32768
	s_waitcnt lgkmcnt(0)
	v_mfma_f32_32x32x16_bf16 v[64:79], v[100:103], v[130:133], v[64:79]
	ds_read_b128 v[100:103], v193 offset:32768
	s_waitcnt lgkmcnt(0)
	v_and_b32_e32 v190, 63, v195
	v_lshlrev_b32_e32 v191, 4, v195
	v_and_b32_e32 v192, 31, v195
	v_bfe_u32 v193, v195, 5, 1
	v_mfma_f32_32x32x16_bf16 v[64:79], v[100:103], v[134:137], v[64:79]
	v_mfma_f32_32x32x16_bf16 v[96:111], v[96:99], v[142:145], 0
	s_nop 10
	v_exp_f32_e32 v72, v80
	v_exp_f32_e32 v80, v81
	v_exp_f32_e32 v73, v82
	v_exp_f32_e32 v81, v83
	v_exp_f32_e32 v74, v84
	v_add_f32_e32 v84, 0, v72
	v_exp_f32_e32 v82, v85
	v_mfma_f32_32x32x16_bf16 v[96:111], v[170:173], v[138:141], v[96:111]
	v_add_f32_e32 v84, v80, v84
	v_exp_f32_e32 v75, v86
	v_add_f32_e32 v84, v73, v84
	v_exp_f32_e32 v83, v87
	v_add_f32_e32 v84, v81, v84
	v_exp_f32_e32 v76, v88
	v_add_f32_e32 v84, v74, v84
	v_mfma_f32_32x32x16_bf16 v[96:111], v[162:165], v[112:115], v[96:111]
	v_exp_f32_e32 v85, v89
	v_add_f32_e32 v84, v82, v84
	v_exp_f32_e32 v77, v90
	v_add_f32_e32 v84, v75, v84
	v_exp_f32_e32 v87, v91
	v_add_f32_e32 v84, v83, v84
	v_exp_f32_e32 v78, v92
	v_mfma_f32_32x32x16_bf16 v[96:111], v[166:169], v[116:119], v[96:111]
	v_add_f32_e32 v84, v76, v84
	v_exp_f32_e32 v89, v93
	v_add_f32_e32 v84, v85, v84
	v_exp_f32_e32 v79, v94
	v_add_f32_e32 v84, v77, v84
	v_exp_f32_e32 v90, v95
	v_add_f32_e32 v84, v87, v84
	v_mfma_f32_32x32x16_bf16 v[96:111], v[174:177], v[120:123], v[96:111]
	v_add_f32_e32 v84, v78, v84
	v_add_f32_e32 v84, v89, v84
	v_add_f32_e32 v84, v79, v84
	v_add_f32_e32 v84, v90, v84
	v_lshl_add_u32 v88, v247, 2, s2
	v_cvt_pk_bf16_f32 v72, v72, v80
	v_cvt_pk_bf16_f32 v73, v73, v81
	v_mfma_f32_32x32x16_bf16 v[96:111], v[178:181], v[124:127], v[96:111]
	v_cvt_pk_bf16_f32 v74, v74, v82
	v_cvt_pk_bf16_f32 v75, v75, v83
	v_cvt_pk_bf16_f32 v76, v76, v85
	v_cvt_pk_bf16_f32 v77, v77, v87
	v_cvt_pk_bf16_f32 v78, v78, v89
	v_cvt_pk_bf16_f32 v79, v79, v90
	s_nop 0
	v_permlane32_swap_b32_e32 v72, v74
	v_mfma_f32_32x32x16_bf16 v[96:111], v[182:185], v[130:133], v[96:111]
	v_permlane32_swap_b32_e32 v73, v75
	v_permlane32_swap_b32_e32 v76, v78
	v_permlane32_swap_b32_e32 v77, v79
; #define SBAR() __builtin_amdgcn_sched_barrier(0)
; __device__ __forceinline__ void finishSM(f32x16& p0, f32x16& p1, float alpha, float& l_reg, bf16x8& pa0, bf16x8& pa1, bf16x8& pa2, bf16x8& pa3) {
;   for (int r = 0; r < 16; ++r) p1[r] = __builtin_amdgcn_exp2f(p1[r]);
;   float ps = 0; for (int r = 0; r < 16; ++r) ps += p0[r]; for (int r = 0; r < 16; ++r) ps += p1[r];
;   { auto rr = __builtin_amdgcn_permlane32_swap(__float_as_uint(ps), __float_as_uint(ps), false, false);
;     ps = __uint_as_float(rr[0]) + __uint_as_float(rr[1]); }
;   l_reg = l_reg * alpha + ps;
;     ...
;   PK4(p0, 0, pa0); PK4(p0, 8, pa1); PK4(p1, 0, pa2); PK4(p1, 8, pa3);
;     ...
; }
; template <int D0, int BOFF> __device__ __forceinline__ void pv_one_i(f32x16& od, int vb, bf16x8 pa0, bf16x8 pa1, bf16x8 pa2, bf16x8 pa3) {
;   const s16x4 l0 = tr_read<BOFF + v_rd_off(D0, 0, 0)>(vb), h0 = tr_read<BOFF + v_rd_off(D0, 0, 1)>(vb), l1 = tr_read<BOFF + v_rd_off(D0, 1, 0)>(vb), h1 = tr_read<BOFF + v_rd_off(D0, 1, 1)>(vb);
;   const s16x4 l2 = tr_read<BOFF + v_rd_off(D0, 2, 0)>(vb), h2 = tr_read<BOFF + v_rd_off(D0, 2, 1)>(vb), l3 = tr_read<BOFF + v_rd_off(D0, 3, 0)>(vb), h3 = tr_read<BOFF + v_rd_off(D0, 3, 1)>(vb);
;   asm volatile("s_waitcnt lgkmcnt(0)" ::: "memory"); SBAR();
;     ...
;   od = __builtin_amdgcn_mfma_f32_32x32x16_bf16(pa0, PK(l0, h0), od, 0, 0, 0);
;   od = __builtin_amdgcn_mfma_f32_32x32x16_bf16(pa1, PK(l1, h1), od, 0, 0, 0);
;   od = __builtin_amdgcn_mfma_f32_32x32x16_bf16(pa2, PK(l2, h2), od, 0, 0, 0);
;   od = __builtin_amdgcn_mfma_f32_32x32x16_bf16(pa3, PK(l3, h3), od, 0, 0, 0);
;     ...
; }
; template <int BOFF> __device__ __forceinline__ void pv_i(f32x16* o, int vb, bf16x8 pa0, bf16x8 pa1, bf16x8 pa2, bf16x8 pa3) {
;   pv_one_i<0, BOFF>(o[0], vb, pa0, pa1, pa2, pa3); pv_one_i<1, BOFF>(o[1], vb, pa0, pa1, pa2, pa3); pv_one_i<2, BOFF>(o[2], vb, pa0, pa1, pa2, pa3); pv_one_i<3, BOFF>(o[3], vb, pa0, pa1, pa2, pa3);
; }
	v_mfma_f32_32x32x16_bf16 v[96:111], v[186:189], v[134:137], v[96:111]
	s_nop 11
	v_exp_f32_e32 v91, v96
	v_exp_f32_e32 v92, v97
	v_exp_f32_e32 v93, v98
	v_exp_f32_e32 v94, v99
	v_exp_f32_e32 v95, v100
	v_add_f32_e32 v84, v84, v91
	v_exp_f32_e32 v96, v101
	v_add_f32_e32 v84, v92, v84
	v_exp_f32_e32 v97, v102
	v_add_f32_e32 v84, v93, v84
	v_exp_f32_e32 v98, v103
	v_add_f32_e32 v84, v94, v84
	v_exp_f32_e32 v99, v104
	v_add_f32_e32 v84, v95, v84
	v_exp_f32_e32 v100, v105
	v_add_f32_e32 v84, v96, v84
	v_exp_f32_e32 v101, v106
	v_add_f32_e32 v84, v97, v84
	v_exp_f32_e32 v102, v107
	v_add_f32_e32 v84, v98, v84
	v_exp_f32_e32 v103, v108
	v_add_f32_e32 v84, v99, v84
	v_exp_f32_e32 v104, v109
	v_add_f32_e32 v84, v100, v84
	v_exp_f32_e32 v105, v110
	v_add_f32_e32 v84, v101, v84
	v_exp_f32_e32 v106, v111
	v_add_f32_e32 v84, v102, v84
	v_add_f32_e32 v84, v103, v84
	v_add_f32_e32 v84, v104, v84
	v_add_f32_e32 v84, v105, v84
	v_add_f32_e32 v84, v106, v84
	v_mov_b32_e32 v86, v84
	s_nop 1
	v_permlane32_swap_b32_e32 v84, v86
	v_cvt_pk_bf16_f32 v80, v91, v92
	v_cvt_pk_bf16_f32 v81, v93, v94
	v_cvt_pk_bf16_f32 v82, v95, v96
	v_cvt_pk_bf16_f32 v83, v97, v98
	v_cvt_pk_bf16_f32 v90, v99, v100
	v_cvt_pk_bf16_f32 v91, v101, v102
	v_cvt_pk_bf16_f32 v92, v103, v104
	v_cvt_pk_bf16_f32 v93, v105, v106
	s_nop 0
	v_permlane32_swap_b32_e32 v80, v82
	v_permlane32_swap_b32_e32 v81, v83
	v_permlane32_swap_b32_e32 v90, v92
	v_permlane32_swap_b32_e32 v91, v93
	ds_read_b64_tr_b16 v[94:95], v206 offset:0x4000
	ds_read_b64_tr_b16 v[96:97], v206 offset:0x4800
	ds_read_b64_tr_b16 v[98:99], v206 offset:0x5000
	ds_read_b64_tr_b16 v[100:101], v206 offset:0x5800
	ds_read_b64_tr_b16 v[102:103], v206 offset:0x6000
	ds_read_b64_tr_b16 v[104:105], v206 offset:0x6800
	ds_read_b64_tr_b16 v[106:107], v206 offset:0x7000
	ds_read_b64_tr_b16 v[108:109], v206 offset:0x7800
	s_waitcnt lgkmcnt(0)
	s_nop 0
	v_mfma_f32_32x32x16_bf16 v[0:15], v[72:75], v[94:97], v[0:15]
	ds_read_b64_tr_b16 v[94:95], v206 offset:0x4200
	ds_read_b64_tr_b16 v[96:97], v206 offset:0x4a00
	v_mfma_f32_32x32x16_bf16 v[0:15], v[76:79], v[98:101], v[0:15]
	ds_read_b64_tr_b16 v[98:99], v206 offset:0x5200
	ds_read_b64_tr_b16 v[100:101], v206 offset:0x5a00
	v_mfma_f32_32x32x16_bf16 v[0:15], v[80:83], v[102:105], v[0:15]
	ds_read_b64_tr_b16 v[102:103], v206 offset:0x6200
	ds_read_b64_tr_b16 v[104:105], v206 offset:0x6a00
	v_mfma_f32_32x32x16_bf16 v[0:15], v[90:93], v[106:109], v[0:15]
	ds_read_b64_tr_b16 v[106:107], v206 offset:0x7200
	ds_read_b64_tr_b16 v[108:109], v206 offset:0x7a00
	s_waitcnt lgkmcnt(0)
	v_mfma_f32_32x32x16_bf16 v[16:31], v[72:75], v[94:97], v[16:31]
	ds_read_b64_tr_b16 v[94:95], v206 offset:0x4400
	ds_read_b64_tr_b16 v[96:97], v206 offset:0x4c00
	v_mfma_f32_32x32x16_bf16 v[16:31], v[76:79], v[98:101], v[16:31]
	ds_read_b64_tr_b16 v[98:99], v206 offset:0x5400
	ds_read_b64_tr_b16 v[100:101], v206 offset:0x5c00
	v_mfma_f32_32x32x16_bf16 v[16:31], v[80:83], v[102:105], v[16:31]
	ds_read_b64_tr_b16 v[102:103], v206 offset:0x6400
	ds_read_b64_tr_b16 v[104:105], v206 offset:0x6c00
	v_mfma_f32_32x32x16_bf16 v[16:31], v[90:93], v[106:109], v[16:31]
	ds_read_b64_tr_b16 v[106:107], v206 offset:0x7400
	ds_read_b64_tr_b16 v[108:109], v206 offset:0x7c00
	s_waitcnt lgkmcnt(0)
	v_mfma_f32_32x32x16_bf16 v[32:47], v[72:75], v[94:97], v[32:47]
	ds_read_b64_tr_b16 v[94:95], v206 offset:0x4600
	ds_read_b64_tr_b16 v[96:97], v206 offset:0x4e00
	v_mfma_f32_32x32x16_bf16 v[32:47], v[76:79], v[98:101], v[32:47]
	ds_read_b64_tr_b16 v[98:99], v206 offset:0x5600
	ds_read_b64_tr_b16 v[100:101], v206 offset:0x5e00
	v_mfma_f32_32x32x16_bf16 v[32:47], v[80:83], v[102:105], v[32:47]
	ds_read_b64_tr_b16 v[102:103], v206 offset:0x6600
	ds_read_b64_tr_b16 v[104:105], v206 offset:0x6e00
	v_mfma_f32_32x32x16_bf16 v[32:47], v[90:93], v[106:109], v[32:47]
	ds_read_b64_tr_b16 v[106:107], v206 offset:0x7600
	ds_read_b64_tr_b16 v[108:109], v206 offset:0x7e00
	s_waitcnt lgkmcnt(0)
; #define SBAR() __builtin_amdgcn_sched_barrier(0)
; __device__ __forceinline__ int crow(int r, int hi) { return (r & 3) + 8 * (r >> 2) + 4 * hi; }
; #define NOP_() do { } while (0)
; template <bool PARTIAL, bool FIXED> ...
;     ...
;   HALF_A(2, 1, do { if (mask_last) { asm volatile("; masked tail tile" ::: "memory"); const float NEG = -INFINITY; \
;       _Pragma("unroll") for (int r = 8; r < 16; ++r) pA0[r] = NEG; _Pragma("unroll") for (int r = 0; r < 16; ++r) pA1[r] = NEG; } } while (0), NOP_(), NOP_());
;     ...
;   SBAR(); finishSM(pA0, pA1, alA, l_reg, pa0, pa1, pa2, pa3); SBAR();
;   pv_i<2 * 16384>(o, vbi, pa0, pa1, pa2, pa3);
;     ...
;   if (PARTIAL) {
;     if (wid < 2) { float* po = PO + (wid * QBLK) * 128;
; #pragma unroll
;       for (int r = 0; r < 16; ++r) { const int orow = crow(r, hi);
; #pragma unroll
;         for (int d0 = 0; d0 < 4; ++d0) po[orow * 128 + d0 * 32 + r32] = o[d0][r]; }
;       if (hi == 0) { PO[8192 + (wid * QBLK + r32) * 2] = m_reg; PO[8192 + (wid * QBLK + r32) * 2 + 1] = l_reg; } }
;     __syncthreads();
;     return;
;   }
;   if (hi == 0) li_l[r32] = l_reg; asm volatile("s_waitcnt lgkmcnt(0)" ::: "memory");
	v_mfma_f32_32x32x16_bf16 v[48:63], v[72:75], v[94:97], v[48:63]
	v_exp_f32_e32 v64, v64
	v_exp_f32_e32 v65, v65
	v_exp_f32_e32 v66, v66
	v_exp_f32_e32 v67, v67
	v_exp_f32_e32 v68, v68
	v_exp_f32_e32 v69, v69
	v_exp_f32_e32 v70, v70
	v_mfma_f32_32x32x16_bf16 v[48:63], v[76:79], v[98:101], v[48:63]
	v_exp_f32_e32 v71, v71
	v_mfma_f32_32x32x16_bf16 v[48:63], v[80:83], v[102:105], v[48:63]
	v_mfma_f32_32x32x16_bf16 v[48:63], v[90:93], v[106:109], v[48:63]
	v_add_f32_e32 v72, 0, v64
	v_add_f32_e32 v72, v65, v72
	v_add_f32_e32 v72, v66, v72
	v_add_f32_e32 v72, v67, v72
	v_add_f32_e32 v72, v68, v72
	v_add_f32_e32 v72, v69, v72
	v_add_f32_e32 v72, v70, v72
	v_add_f32_e32 v72, v71, v72
	v_add_f32_e32 v85, 0, v72
	v_mov_b32_e32 v87, v85
	s_nop 1
	v_permlane32_swap_b32_e32 v85, v87
	v_cvt_pk_bf16_f32 v64, v64, v65
	v_cvt_pk_bf16_f32 v65, v66, v67
	v_cvt_pk_bf16_f32 v66, v68, v69
	v_cvt_pk_bf16_f32 v67, v70, v71
	v_cvt_pk_bf16_f32 v68, v129, v129
	v_cvt_pk_bf16_f32 v69, v129, v129
	v_cvt_pk_bf16_f32 v70, v129, v129
	v_cvt_pk_bf16_f32 v71, v129, v129
	v_cvt_pk_bf16_f32 v72, v129, v129
	v_cvt_pk_bf16_f32 v73, v129, v129
	v_cvt_pk_bf16_f32 v74, v129, v129
	v_cvt_pk_bf16_f32 v75, v129, v129
	v_cvt_pk_bf16_f32 v76, v129, v129
	v_cvt_pk_bf16_f32 v77, v129, v129
	v_cvt_pk_bf16_f32 v78, v129, v129
	v_cvt_pk_bf16_f32 v79, v129, v129
	s_nop 0
	v_permlane32_swap_b32_e32 v64, v66
	v_permlane32_swap_b32_e32 v65, v67
	v_permlane32_swap_b32_e32 v68, v70
	v_permlane32_swap_b32_e32 v69, v71
	v_permlane32_swap_b32_e32 v72, v74
	v_permlane32_swap_b32_e32 v73, v75
	v_permlane32_swap_b32_e32 v76, v78
	v_permlane32_swap_b32_e32 v77, v79
	ds_read_b64_tr_b16 v[80:81], v206 offset:0x8000
	ds_read_b64_tr_b16 v[82:83], v206 offset:0x8800
	ds_read_b64_tr_b16 v[90:91], v206 offset:0x9000
	ds_read_b64_tr_b16 v[92:93], v206 offset:0x9800
	ds_read_b64_tr_b16 v[94:95], v206 offset:0xa000
	ds_read_b64_tr_b16 v[96:97], v206 offset:0xa800
	ds_read_b64_tr_b16 v[98:99], v206 offset:0xb000
	ds_read_b64_tr_b16 v[100:101], v206 offset:0xb800
	s_waitcnt lgkmcnt(0)
	s_nop 0
	v_mfma_f32_32x32x16_bf16 v[0:15], v[64:67], v[80:83], v[0:15]
	ds_read_b64_tr_b16 v[80:81], v206 offset:0x8200
	ds_read_b64_tr_b16 v[82:83], v206 offset:0x8a00
	v_mfma_f32_32x32x16_bf16 v[0:15], v[68:71], v[90:93], v[0:15]
	ds_read_b64_tr_b16 v[90:91], v206 offset:0x9200
	ds_read_b64_tr_b16 v[92:93], v206 offset:0x9a00
	v_mfma_f32_32x32x16_bf16 v[0:15], v[72:75], v[94:97], v[0:15]
	ds_read_b64_tr_b16 v[94:95], v206 offset:0xa200
	ds_read_b64_tr_b16 v[96:97], v206 offset:0xaa00
	v_mfma_f32_32x32x16_bf16 v[0:15], v[76:79], v[98:101], v[0:15]
	ds_read_b64_tr_b16 v[98:99], v206 offset:0xb200
	ds_read_b64_tr_b16 v[100:101], v206 offset:0xba00
	s_waitcnt lgkmcnt(0)
	v_mfma_f32_32x32x16_bf16 v[16:31], v[64:67], v[80:83], v[16:31]
	ds_read_b64_tr_b16 v[80:81], v206 offset:0x8400
	ds_read_b64_tr_b16 v[82:83], v206 offset:0x8c00
	v_mfma_f32_32x32x16_bf16 v[16:31], v[68:71], v[90:93], v[16:31]
	ds_read_b64_tr_b16 v[90:91], v206 offset:0x9400
	ds_read_b64_tr_b16 v[92:93], v206 offset:0x9c00
	v_mfma_f32_32x32x16_bf16 v[16:31], v[72:75], v[94:97], v[16:31]
	ds_read_b64_tr_b16 v[94:95], v206 offset:0xa400
	ds_read_b64_tr_b16 v[96:97], v206 offset:0xac00
	v_mfma_f32_32x32x16_bf16 v[16:31], v[76:79], v[98:101], v[16:31]
	ds_read_b64_tr_b16 v[98:99], v206 offset:0xb400
	ds_read_b64_tr_b16 v[100:101], v206 offset:0xbc00
	s_waitcnt lgkmcnt(0)
	v_mfma_f32_32x32x16_bf16 v[32:47], v[64:67], v[80:83], v[32:47]
	ds_read_b64_tr_b16 v[80:81], v206 offset:0x8600
	ds_read_b64_tr_b16 v[82:83], v206 offset:0x8e00
	v_mfma_f32_32x32x16_bf16 v[32:47], v[68:71], v[90:93], v[32:47]
	ds_read_b64_tr_b16 v[90:91], v206 offset:0x9600
	ds_read_b64_tr_b16 v[92:93], v206 offset:0x9e00
	v_mfma_f32_32x32x16_bf16 v[32:47], v[72:75], v[94:97], v[32:47]
	ds_read_b64_tr_b16 v[94:95], v206 offset:0xa600
	ds_read_b64_tr_b16 v[96:97], v206 offset:0xae00
	v_mfma_f32_32x32x16_bf16 v[32:47], v[76:79], v[98:101], v[32:47]
	ds_read_b64_tr_b16 v[98:99], v206 offset:0xb600
	ds_read_b64_tr_b16 v[100:101], v206 offset:0xbe00
	s_waitcnt lgkmcnt(0)
	v_mfma_f32_32x32x16_bf16 v[48:63], v[64:67], v[80:83], v[48:63]
	v_cmp_gt_u32_e32 vcc, 32, v190
	v_mfma_f32_32x32x16_bf16 v[48:63], v[68:71], v[90:93], v[48:63]
	v_mfma_f32_32x32x16_bf16 v[48:63], v[72:75], v[94:97], v[48:63]
	v_mfma_f32_32x32x16_bf16 v[48:63], v[76:79], v[98:101], v[48:63]
	s_and_saveexec_b64 s[28:29], vcc
	s_cbranch_execz .LBB0_309
	v_add_f32_e32 v64, v128, v218
	v_add_f32_e32 v66, v215, v64
	v_pk_add_f32 v[64:65], v[84:85], v[86:87]
	v_lshl_add_u32 v67, v192, 2, v88
	v_add_f32_e32 v64, v66, v64
	v_add_f32_e32 v64, v64, v65
	ds_write_b32 v67, v64
	s_branch .LBB0_309
